# phase0: cvec/mod item loads batched, w_in transposes software-pipelined; diff/nsa epilogue loads hoisted; p1 rewritten; nsa per-xcd queues
# speedup vs baseline: 1.0284x; 1.0284x over previous
; DI void transpose_item(const float* src, int ldsrc, int nsrc0, int nvalid, int k0, u16* dst, int lddst, int n0,
;                        char* smem, int tid) {
;   float* tile = (float*)smem;
;   __syncthreads();
; #pragma unroll
;   for (int i = 0; i < 2; ++i) {
;     int id = tid + NTHR * i, k = id >> 4, c4 = id & 15;
;     float4 v = make_float4(0.f, 0.f, 0.f, 0.f);
;     if (c4 * 4 < nvalid) v = *(const float4*)(src + (size_t)(k0 + k) * ldsrc + nsrc0 + c4 * 4);
;     float* t = tile + k * 65 + c4 * 4;
;     t[0] = v.x; t[1] = v.y; t[2] = v.z; t[3] = v.w;
; DI void phase_prep(const Params& p, char* smem, int tid) {
;   constexpr int N_WIN = 32 * 188, N_WB = 1024, N_WO = 1024, N_W1 = 256, N_W2 = 8;
;   constexpr int O_WB = N_WIN, O_WO = O_WB + N_WB, O_W1K = O_WO + N_WO, O_W1V = O_W1K + N_W1, O_W2K = O_W1V + N_W1,
;                 O_W2V = O_W2K + N_W2, O_MOD = O_W2V + N_W2, O_CV = O_MOD + 96, O_TAB = O_CV + 8, O_END = O_TAB + 32;
;   for (int it = blockIdx.x; it < O_END; it += gridDim.x) {
;     if (it < O_WB) {
;       int kt = it & 31, nt = it >> 5, n0 = nt * 64, src0, nv;
;       if (n0 < 7680) { src0 = n0; nv = 64; }
;       else if (n0 < 11776) { src0 = n0 + 24; nv = 64; }
;       else if (n0 == 11776) { src0 = 7680; nv = 24; }
;       else { src0 = 0; nv = 0; }
;       transpose_item(p.w_in, 11800, src0, nv, kt * 64, p.WtIn, DM, n0, smem, tid);
_Z11mega_kernel6Params:
	s_load_dwordx2 s[16:17], s[0:1], 0x188
	s_load_dword s91, s[0:1], 0x190
	s_mov_b32 s90, s2
	s_mov_b64 s[92:93], s[0:1]
	v_and_b32_e32 v197, 0x3ff, v0
	s_add_u32 s22, s92, 0x190
	v_or_b32_e32 v1, s90, v197
	s_addc_u32 s23, s93, 0
	v_cmp_eq_u32_e32 vcc, 0, v1
	s_and_saveexec_b64 s[0:1], vcc
	s_cbranch_execz .LBB0_2
	v_mov_b32_e32 v1, 0
	v_mov_b32_e32 v2, 0
	v_mov_b32_e32 v3, 0
	v_mov_b32_e32 v4, 0
	v_mov_b32_e32 v5, 0
	s_waitcnt lgkmcnt(0)
	global_store_dword v1, v1, s[16:17] offset:64 sc1
	global_store_dwordx4 v1, v[2:5], s[16:17] offset:80 sc1
	global_store_dwordx4 v1, v[2:5], s[16:17] offset:96 sc1
	global_store_dwordx4 v1, v[2:5], s[16:17] offset:112 sc1
	global_store_dwordx4 v1, v[2:5], s[16:17] offset:128 sc1
.LBB0_2:
	s_or_b64 exec, exec, s[0:1]
	v_mov_b32_e32 v10, v197
	s_waitcnt lgkmcnt(0)
	v_writelane_b32 v255, s16, 0
	s_cmpk_gt_i32 s90, 0x2217
	s_nop 0
	v_writelane_b32 v255, s17, 1
	s_cbranch_scc1 .LBB0_60
	s_movk_i32 s0, 0x100
	v_cmp_gt_i32_e64 s[14:15], s0, v10
	s_movk_i32 s0, 0x3ff
	v_cmp_lt_i32_e32 vcc, s0, v10
	s_movk_i32 s0, 0x2000
	v_cmp_gt_i32_e64 s[6:7], s0, v10
	v_ashrrev_i32_e32 v5, 6, v10
	s_movk_i32 s0, 0x1800
	v_and_b32_e32 v1, 63, v10
	v_lshlrev_b32_e32 v8, 8, v5
	v_lshl_add_u32 v17, v5, 10, 0
	v_mul_lo_u32 v5, v5, s0
	v_lshlrev_b32_e32 v3, 3, v10
	v_and_b32_e32 v6, 0x3fffffc0, v10
	v_or_b32_e32 v38, v5, v1
	v_add_u32_e32 v5, 0x200, v10
	s_load_dwordx4 s[16:19], s[92:93], 0x148
	v_lshlrev_b32_e32 v9, 2, v1
	v_lshlrev_b32_e32 v6, 2, v6
	v_ashrrev_i32_e32 v40, 4, v10
	s_movk_i32 s0, 0x104
	v_ashrrev_i32_e32 v42, 4, v5
	v_ashrrev_i32_e32 v44, 3, v10
	v_and_b32_e32 v16, 56, v3
	v_add3_u32 v37, 0, v6, v9
	v_mul_lo_u32 v41, v40, s0
	v_mul_lo_u32 v43, v42, s0
	v_mul_u32_u24_e32 v5, 0x104, v16
	v_lshlrev_b32_e32 v6, 2, v44
	s_load_dwordx2 s[44:45], s[92:93], 0xc8
	s_load_dwordx4 s[0:3], s[92:93], 0x8
	v_mov_b32_e32 v15, 0
	v_add3_u32 v45, 0, v5, v6
	v_and_b32_e32 v5, 0x7f, v10
	v_lshlrev_b32_e32 v14, 10, v5
	v_lshlrev_b32_e32 v6, 1, v5
	v_mov_b32_e32 v7, v15
	v_and_b32_e32 v2, 0xfffffe00, v3
	s_waitcnt lgkmcnt(0)
	v_lshl_add_u64 v[18:19], s[16:17], 0, v[6:7]
	v_lshl_add_u64 v[20:21], s[18:19], 0, v[14:15]
	s_load_dwordx4 s[16:19], s[92:93], 0x88
	s_load_dwordx2 s[10:11], s[92:93], 0x28
	v_or_b32_e32 v46, 0x1ff, v3
	v_ashrrev_i32_e32 v3, 31, v2
	s_movk_i32 s81, 0x6000
	s_load_dwordx8 s[24:31], s[92:93], 0x168
	s_load_dwordx8 s[36:43], s[92:93], 0xa8
	v_lshlrev_b32_e32 v4, 2, v10
	v_mov_b32_e32 v6, s0
	v_mov_b32_e32 v7, s1
	v_add_u32_e32 v47, -1, v2
	v_lshlrev_b64 v[28:29], 2, v[2:3]
	v_lshlrev_b64 v[30:31], 10, v[2:3]
	v_mad_i64_i32 v[2:3], s[0:1], v8, s81, 0
	v_and_b32_e32 v12, 60, v4
	v_or_b32_e32 v2, v2, v9
	v_add_u32_e32 v13, 0, v4
	v_lshlrev_b32_e32 v4, 2, v12
	v_mov_b32_e32 v5, v15
	s_lshl_b32 s33, s90, 6
	v_ashrrev_i32_e32 v11, 31, v10
	v_lshl_add_u64 v[34:35], s[2:3], 0, v[2:3]
	s_mov_b32 s2, 0x471b3a95
	s_mov_b32 s46, 0x3b39803f
	s_mov_b32 s48, 0xfefa39ef
	s_mov_b32 s50, 0xfca7ab0c
	s_mov_b32 s52, 0x6a5dcb37
	s_mov_b32 s54, 0x623fde64
	s_mov_b32 s56, 0x7c89e6b0
	s_mov_b32 s58, 0x14761f6e
	s_mov_b32 s60, 0x1852b7b0
	s_mov_b32 s62, 0x11122322
	s_mov_b32 s64, 0x555502a1
	s_mov_b32 s66, 0x55555511
	s_mov_b32 s68, 11
	s_mov_b32 s70, 0
	s_mov_b32 s72, 0
	s_mov_b32 s74, 0x6dc9c883
	s_mov_b32 s34, 0
	v_cmp_gt_i32_e64 s[4:5], 64, v10
	v_add_u32_e32 v36, v17, v9
	v_add_u32_e32 v39, 0, v4
	v_cmp_gt_u32_e64 s[8:9], 24, v12
	s_waitcnt lgkmcnt(0)
	v_lshl_add_u64 v[22:23], s[18:19], 0, v[4:5]
	v_lshl_add_u64 v[24:25], s[16:17], 0, v[4:5]
	v_lshl_add_u64 v[26:27], s[10:11], 0, v[4:5]
	v_or_b32_e32 v30, v30, v9
	s_lshl_b32 s80, s91, 6
	v_add_u32_e32 v48, 0xfffffe00, v10
	v_lshl_add_u64 v[32:33], v[10:11], 2, v[6:7]
	s_add_i32 s0, s33, 0xfff79c00
	s_mov_b32 s3, 0x4032ee7b
	s_mov_b32 s47, 0x3c7abc9e
	s_mov_b32 s49, 0x3fe62e42
	s_mov_b32 s51, 0x3e928af3
	s_mov_b32 s53, 0x3e5ade15
	s_mov_b32 s55, 0x3ec71dee
	s_mov_b32 s57, 0x3efa0199
	s_mov_b32 s59, 0x3f2a01a0
	s_mov_b32 s61, 0x3f56c16c
	s_mov_b32 s63, 0x3f811111
	s_mov_b32 s65, 0x3fa55555
	s_mov_b32 s67, 0x3fc55555
	s_mov_b32 s69, 0x3fe00000
	s_mov_b32 s71, 0x40900000
	s_mov_b32 s73, 0xc090cc00
	s_mov_b32 s75, 0x3fc45f30
	s_xor_b64 s[76:77], vcc, -1
	s_movk_i32 s82, 0x68
	s_mov_b32 s83, 0xc000
	s_mov_b32 s84, 0x12000
	s_movk_i32 s85, 0x70
	s_mov_b32 s86, 0xb860
	v_mov_b32_e32 v50, v15
	v_mov_b32_e32 v51, v15
	v_mov_b32_e32 v11, 0x7ff00000
	s_load_dwordx2 s[98:99], s[92:93], 0x28
	s_load_dwordx2 s[100:101], s[92:93], 0xa8
	s_and_b32 s32, s90, 31
	v_and_b32_e32 v121, 15, v197
	v_lshrrev_b32_e32 v119, 4, v197
	s_lshl_b32 s32, s32, 6
	v_add_u32_e32 v120, s32, v119
	v_mov_b32_e32 v108, 0x2e18
	v_mul_lo_u32 v120, v120, v108
	v_lshl_add_u32 v120, v121, 2, v120
	v_lshlrev_b32_e32 v108, 2, v120
	v_add_u32_e32 v109, 0x170c00, v108
	v_mov_b32_e32 v120, 0x104
	v_mul_lo_u32 v119, v119, v120
	v_lshl_add_u32 v110, v121, 4, v119
	v_add_u32_e32 v111, 0x2080, v110
	v_add_u32_e32 v112, 0x4200, v110
	v_add_u32_e32 v113, 0x4200, v111
	v_and_b32_e32 v119, 7, v197
	v_lshrrev_b32_e32 v120, 3, v197
	v_mov_b32_e32 v114, 0x820
	v_mul_lo_u32 v114, v119, v114
	v_lshl_add_u32 v114, v120, 2, v114
	v_add_u32_e32 v115, 0x400, v114
	v_add_u32_e32 v116, 0x4200, v114
	v_add_u32_e32 v117, 0x4200, v115
	s_lshl_b32 s32, s32, 1
	v_lshlrev_b32_e32 v118, 4, v119
	v_lshl_add_u32 v118, v120, 12, v118
	v_add_u32_e32 v118, s32, v118
	s_mov_b32 s88, s90
	s_waitcnt lgkmcnt(0)
	s_lshr_b32 s32, s88, 5
	s_lshl_b32 s94, s32, 18
	s_add_u32 s94, s100, s94
	s_addc_u32 s95, s101, 0
	s_lshl_b32 s32, s32, 6
	s_cmpk_lt_u32 s32, 0x2e00
	s_cbranch_scc0 .Lp0_special_0
	s_cmpk_ge_u32 s32, 0x1e00
	s_cselect_b32 vcc_lo, 24, 0
	s_add_i32 s32, s32, vcc_lo
; DI void transpose_item(const float* src, int ldsrc, int nsrc0, int nvalid, int k0, u16* dst, int lddst, int n0,
;                        char* smem, int tid) {
;     ...
;   for (int i = 0; i < 2; ++i) {
;     int id = tid + NTHR * i, k = id >> 4, c4 = id & 15;
;     float4 v = make_float4(0.f, 0.f, 0.f, 0.f);
;     if (c4 * 4 < nvalid) v = *(const float4*)(src + (size_t)(k0 + k) * ldsrc + nsrc0 + c4 * 4);
;     float* t = tile + k * 65 + c4 * 4;
;     t[0] = v.x; t[1] = v.y; t[2] = v.z; t[3] = v.w;
; DI void phase_prep(const Params& p, char* smem, int tid) {
;     ...
;   for (int it = blockIdx.x; it < O_END; it += gridDim.x) {
;     if (it < O_WB) {
;       int kt = it & 31, nt = it >> 5, n0 = nt * 64, src0, nv;
;       if (n0 < 7680) { src0 = n0; nv = 64; }
;       else if (n0 < 11776) { src0 = n0 + 24; nv = 64; }
;       else if (n0 == 11776) { src0 = 7680; nv = 24; }
;       else { src0 = 0; nv = 0; }
;       transpose_item(p.w_in, 11800, src0, nv, kt * 64, p.WtIn, DM, n0, smem, tid);
.Lp0_issue_0:
	s_lshl_b32 s32, s32, 2
	s_add_u32 vcc_lo, s98, s32
	s_addc_u32 vcc_hi, s99, 0
	global_load_dwordx4 v[80:83], v108, vcc
	global_load_dwordx4 v[84:87], v109, vcc
	s_mov_b64 exec, -1
	s_branch .Lp0_loaded_0
.Lp0_special_0:
	v_mov_b32_e32 v80, 0
	v_mov_b32_e32 v81, 0
	v_mov_b32_e32 v82, 0
	v_mov_b32_e32 v83, 0
	v_mov_b32_e32 v84, 0
	v_mov_b32_e32 v85, 0
	v_mov_b32_e32 v86, 0
	v_mov_b32_e32 v87, 0
	s_cmpk_eq_u32 s32, 0x2e00
	s_cbranch_scc1 .Lp0_gate_0
	s_waitcnt vmcnt(0)
	s_branch .Lp0_loaded_0
.Lp0_gate_0:
	s_movk_i32 s32, 0x1e00
	v_cmp_gt_u32_e32 vcc, 6, v121
	s_and_b64 exec, exec, vcc
	s_branch .Lp0_issue_0
.Lp0_loaded_0:
.Lp0_top:
	s_add_i32 s89, s88, s91
	s_cmpk_lt_u32 s89, 0x1780
	s_cbranch_scc0 .Lp0_lastA
	s_lshr_b32 s32, s89, 5
	s_lshl_b32 s96, s32, 18
	s_add_u32 s96, s100, s96
	s_addc_u32 s97, s101, 0
	s_lshl_b32 s32, s32, 6
	s_cmpk_lt_u32 s32, 0x2e00
	s_cbranch_scc0 .Lp0_special_1
	s_cmpk_ge_u32 s32, 0x1e00
	s_cselect_b32 vcc_lo, 24, 0
	s_add_i32 s32, s32, vcc_lo
.Lp0_issue_1:
	s_lshl_b32 s32, s32, 2
	s_add_u32 vcc_lo, s98, s32
	s_addc_u32 vcc_hi, s99, 0
	global_load_dwordx4 v[88:91], v108, vcc
	global_load_dwordx4 v[92:95], v109, vcc
	s_mov_b64 exec, -1
	s_branch .Lp0_loaded_1
.Lp0_special_1:
	v_mov_b32_e32 v88, 0
	v_mov_b32_e32 v89, 0
	v_mov_b32_e32 v90, 0
	v_mov_b32_e32 v91, 0
	v_mov_b32_e32 v92, 0
	v_mov_b32_e32 v93, 0
	v_mov_b32_e32 v94, 0
	v_mov_b32_e32 v95, 0
	s_cmpk_eq_u32 s32, 0x2e00
	s_cbranch_scc1 .Lp0_gate_1
	s_waitcnt vmcnt(0)
	s_branch .Lp0_loaded_1

; DI unsigned pk2(float a, float b) { f32x2 v = {a, b}; bf16x2_t r = __builtin_convertvector(v, bf16x2_t); return __builtin_bit_cast(unsigned, r); }
; DI void transpose_item(const float* src, int ldsrc, int nsrc0, int nvalid, int k0, u16* dst, int lddst, int n0,
;                        char* smem, int tid) {
;   float* tile = (float*)smem;
;   __syncthreads();
; #pragma unroll
;   for (int i = 0; i < 2; ++i) {
;     int id = tid + NTHR * i, k = id >> 4, c4 = id & 15;
;     float4 v = make_float4(0.f, 0.f, 0.f, 0.f);
;     if (c4 * 4 < nvalid) v = *(const float4*)(src + (size_t)(k0 + k) * ldsrc + nsrc0 + c4 * 4);
;     float* t = tile + k * 65 + c4 * 4;
;     t[0] = v.x; t[1] = v.y; t[2] = v.z; t[3] = v.w;
;   }
;   __syncthreads();
;   {
;     int n = tid >> 3, kc = tid & 7;
;     const float* t = tile + (kc * 8) * 65 + n;
;     uint4 w;
;     w.x = pk2(t[0], t[65]); w.y = pk2(t[130], t[195]); w.z = pk2(t[260], t[325]); w.w = pk2(t[390], t[455]);
;     *(uint4*)(dst + (size_t)(n0 + n) * lddst + k0 + kc * 8) = w;
.Lp0_loaded_1:
	s_waitcnt vmcnt(2)
	ds_write2_b32 v110, v80, v81 offset1:1
	ds_write2_b32 v110, v82, v83 offset0:2 offset1:3
	ds_write2_b32 v111, v84, v85 offset1:1
	ds_write2_b32 v111, v86, v87 offset0:2 offset1:3
	s_waitcnt lgkmcnt(0)
	s_barrier
	ds_read2_b32 v[96:97], v114 offset1:65
	ds_read2_b32 v[98:99], v114 offset0:130 offset1:195
	ds_read2_b32 v[100:101], v115 offset0:4 offset1:69
	ds_read2_b32 v[102:103], v115 offset0:134 offset1:199
	s_waitcnt lgkmcnt(3)
	v_cvt_pk_bf16_f32 v104, v96, v97
	s_waitcnt lgkmcnt(2)
	v_cvt_pk_bf16_f32 v105, v98, v99
	s_waitcnt lgkmcnt(1)
	v_cvt_pk_bf16_f32 v106, v100, v101
	s_waitcnt lgkmcnt(0)
	v_cvt_pk_bf16_f32 v107, v102, v103
	global_store_dwordx4 v118, v[104:107], s[94:95]
	s_add_i32 s88, s89, s91
	s_cmpk_lt_u32 s88, 0x1780
	s_cbranch_scc0 .Lp0_lastB
	s_lshr_b32 s32, s88, 5
	s_lshl_b32 s94, s32, 18
	s_add_u32 s94, s100, s94
	s_addc_u32 s95, s101, 0
	s_lshl_b32 s32, s32, 6
	s_cmpk_lt_u32 s32, 0x2e00
	s_cbranch_scc0 .Lp0_special_2
	s_cmpk_ge_u32 s32, 0x1e00
	s_cselect_b32 vcc_lo, 24, 0
	s_add_i32 s32, s32, vcc_lo

; DI unsigned pk2(float a, float b) { f32x2 v = {a, b}; bf16x2_t r = __builtin_convertvector(v, bf16x2_t); return __builtin_bit_cast(unsigned, r); }
; DI void transpose_item(const float* src, int ldsrc, int nsrc0, int nvalid, int k0, u16* dst, int lddst, int n0,
;                        char* smem, int tid) {
;   float* tile = (float*)smem;
;   __syncthreads();
; #pragma unroll
;   for (int i = 0; i < 2; ++i) {
;     int id = tid + NTHR * i, k = id >> 4, c4 = id & 15;
;     float4 v = make_float4(0.f, 0.f, 0.f, 0.f);
;     if (c4 * 4 < nvalid) v = *(const float4*)(src + (size_t)(k0 + k) * ldsrc + nsrc0 + c4 * 4);
;     float* t = tile + k * 65 + c4 * 4;
;     t[0] = v.x; t[1] = v.y; t[2] = v.z; t[3] = v.w;
;   }
;   __syncthreads();
;   {
;     int n = tid >> 3, kc = tid & 7;
;     const float* t = tile + (kc * 8) * 65 + n;
;     uint4 w;
;     w.x = pk2(t[0], t[65]); w.y = pk2(t[130], t[195]); w.z = pk2(t[260], t[325]); w.w = pk2(t[390], t[455]);
;     *(uint4*)(dst + (size_t)(n0 + n) * lddst + k0 + kc * 8) = w;
.Lp0_loaded_2:
	s_waitcnt vmcnt(2)
	ds_write2_b32 v112, v88, v89 offset1:1
	ds_write2_b32 v112, v90, v91 offset0:2 offset1:3
	ds_write2_b32 v113, v92, v93 offset1:1
	ds_write2_b32 v113, v94, v95 offset0:2 offset1:3
	s_waitcnt lgkmcnt(0)
	s_barrier
	ds_read2_b32 v[96:97], v116 offset1:65
	ds_read2_b32 v[98:99], v116 offset0:130 offset1:195
	ds_read2_b32 v[100:101], v117 offset0:4 offset1:69
	ds_read2_b32 v[102:103], v117 offset0:134 offset1:199
	s_waitcnt lgkmcnt(3)
	v_cvt_pk_bf16_f32 v104, v96, v97
	s_waitcnt lgkmcnt(2)
	v_cvt_pk_bf16_f32 v105, v98, v99
	s_waitcnt lgkmcnt(1)
	v_cvt_pk_bf16_f32 v106, v100, v101
	s_waitcnt lgkmcnt(0)
	v_cvt_pk_bf16_f32 v107, v102, v103
	global_store_dwordx4 v118, v[104:107], s[96:97]
	s_branch .Lp0_top
.Lp0_lastA:
	s_waitcnt vmcnt(0)
	ds_write2_b32 v110, v80, v81 offset1:1
	ds_write2_b32 v110, v82, v83 offset0:2 offset1:3
	ds_write2_b32 v111, v84, v85 offset1:1
	ds_write2_b32 v111, v86, v87 offset0:2 offset1:3
	s_waitcnt lgkmcnt(0)
	s_barrier
	ds_read2_b32 v[96:97], v114 offset1:65
	ds_read2_b32 v[98:99], v114 offset0:130 offset1:195
	ds_read2_b32 v[100:101], v115 offset0:4 offset1:69
	ds_read2_b32 v[102:103], v115 offset0:134 offset1:199
	s_waitcnt lgkmcnt(3)
	v_cvt_pk_bf16_f32 v104, v96, v97
	s_waitcnt lgkmcnt(2)
	v_cvt_pk_bf16_f32 v105, v98, v99
	s_waitcnt lgkmcnt(1)
	v_cvt_pk_bf16_f32 v106, v100, v101
	s_waitcnt lgkmcnt(0)
	v_cvt_pk_bf16_f32 v107, v102, v103
	global_store_dwordx4 v118, v[104:107], s[94:95]
	s_mov_b32 s88, s89
	s_branch .Lp0_done
.Lp0_lastB:
	s_waitcnt vmcnt(0)
	ds_write2_b32 v112, v88, v89 offset1:1
	ds_write2_b32 v112, v90, v91 offset0:2 offset1:3
	ds_write2_b32 v113, v92, v93 offset1:1
	ds_write2_b32 v113, v94, v95 offset0:2 offset1:3
	s_waitcnt lgkmcnt(0)
	s_barrier
	ds_read2_b32 v[96:97], v116 offset1:65
	ds_read2_b32 v[98:99], v116 offset0:130 offset1:195
	ds_read2_b32 v[100:101], v117 offset0:4 offset1:69
	ds_read2_b32 v[102:103], v117 offset0:134 offset1:199
	s_waitcnt lgkmcnt(3)
	v_cvt_pk_bf16_f32 v104, v96, v97
	s_waitcnt lgkmcnt(2)
	v_cvt_pk_bf16_f32 v105, v98, v99
	s_waitcnt lgkmcnt(1)
	v_cvt_pk_bf16_f32 v106, v100, v101
	s_waitcnt lgkmcnt(0)
	v_cvt_pk_bf16_f32 v107, v102, v103
	global_store_dwordx4 v118, v[104:107], s[96:97]
.Lp0_done:
	s_lshl_b32 s33, s88, 6
	s_add_i32 s0, s33, 0xfff79c00
	s_mov_b32 s87, s88
	s_branch .LBB0_6

; DI void phase_prep(const Params& p, char* smem, int tid) {
;     ...
;       int i = it - O_CV, kv = i >> 2, col0 = (i & 3) * 64;
;       const float* pe = kv ? p.pe_v : p.pe_k; const float* w1 = kv ? p.w1v : p.w1k;
;       float* red = (float*)smem;
;       __syncthreads();
;       int col = tid & 63, kg = tid >> 6; float a = 0;
;       for (int k = kg * 512; k < kg * 512 + 512; ++k) a += pe[k] * w1[(size_t)k * 256 + col0 + col];
;       red[kg * 64 + col] = a;
;       __syncthreads();
;       if (tid < 64) { float s = 0;
; #pragma unroll
;         for (int g = 0; g < 8; ++g) s += red[g * 64 + tid];
;         p.cvec[kv * 256 + col0 + tid] = s; }
.LBB0_22:
	s_and_b64 vcc, exec, s[10:11]
	s_cbranch_vccz .LBB0_28
	s_lshl_b32 s1, s33, 2
	s_and_b32 s10, s1, 0x300
	s_add_i32 s1, s87, 0xffffde10
	s_cmp_lt_u32 s1, 4
	s_movk_i32 s12, 0x58
	s_cselect_b32 s12, s12, 0x60
	s_cselect_b32 s16, s82, 0x78
	s_add_u32 s12, s92, s12
	s_addc_u32 s13, s93, 0
	s_add_u32 s16, s92, s16
	s_addc_u32 s17, s93, 0
	s_load_dwordx2 s[12:13], s[12:13], 0x0
	s_nop 0
	s_load_dwordx2 s[16:17], s[16:17], 0x0
	s_mov_b32 s11, s34
	v_mov_b32_e32 v6, 0
	v_mov_b32_e32 v7, v47
	s_waitcnt lgkmcnt(0)
	v_lshl_add_u64 v[2:3], s[12:13], 0, v[28:29]
	v_lshl_add_u64 v[4:5], s[16:17], 0, v[30:31]
	v_lshl_add_u64 v[4:5], v[4:5], 0, s[10:11]
	s_mov_b64 s[10:11], 0
	s_barrier
	s_mov_b32 s32, 0
	s_mov_b64 s[12:13], 0x400
	s_mov_b64 s[88:89], 64
.LBB0_24:
	global_load_dword v124, v[2:3], off
	global_load_dword v140, v[4:5], off
	v_lshl_add_u64 v[4:5], v[4:5], 0, s[12:13]
	global_load_dword v125, v[2:3], off offset:4
	global_load_dword v141, v[4:5], off
	v_lshl_add_u64 v[4:5], v[4:5], 0, s[12:13]
	global_load_dword v126, v[2:3], off offset:8
	global_load_dword v142, v[4:5], off
	v_lshl_add_u64 v[4:5], v[4:5], 0, s[12:13]
	global_load_dword v127, v[2:3], off offset:12
	global_load_dword v143, v[4:5], off
	v_lshl_add_u64 v[4:5], v[4:5], 0, s[12:13]
	global_load_dword v128, v[2:3], off offset:16
	global_load_dword v144, v[4:5], off
	v_lshl_add_u64 v[4:5], v[4:5], 0, s[12:13]
	global_load_dword v129, v[2:3], off offset:20
	global_load_dword v145, v[4:5], off
	v_lshl_add_u64 v[4:5], v[4:5], 0, s[12:13]
	global_load_dword v130, v[2:3], off offset:24
	global_load_dword v146, v[4:5], off
	v_lshl_add_u64 v[4:5], v[4:5], 0, s[12:13]
	global_load_dword v131, v[2:3], off offset:28
	global_load_dword v147, v[4:5], off
	v_lshl_add_u64 v[4:5], v[4:5], 0, s[12:13]
	global_load_dword v132, v[2:3], off offset:32
	global_load_dword v148, v[4:5], off
	v_lshl_add_u64 v[4:5], v[4:5], 0, s[12:13]
	global_load_dword v133, v[2:3], off offset:36
	global_load_dword v149, v[4:5], off
	v_lshl_add_u64 v[4:5], v[4:5], 0, s[12:13]
	global_load_dword v134, v[2:3], off offset:40
	global_load_dword v150, v[4:5], off
	v_lshl_add_u64 v[4:5], v[4:5], 0, s[12:13]
	global_load_dword v135, v[2:3], off offset:44
	global_load_dword v151, v[4:5], off
	v_lshl_add_u64 v[4:5], v[4:5], 0, s[12:13]
	global_load_dword v136, v[2:3], off offset:48
	global_load_dword v152, v[4:5], off
	v_lshl_add_u64 v[4:5], v[4:5], 0, s[12:13]
	global_load_dword v137, v[2:3], off offset:52
	global_load_dword v153, v[4:5], off
	v_lshl_add_u64 v[4:5], v[4:5], 0, s[12:13]
	global_load_dword v138, v[2:3], off offset:56
	global_load_dword v154, v[4:5], off
	v_lshl_add_u64 v[4:5], v[4:5], 0, s[12:13]
	global_load_dword v139, v[2:3], off offset:60
	global_load_dword v155, v[4:5], off
	v_lshl_add_u64 v[4:5], v[4:5], 0, s[12:13]
	v_lshl_add_u64 v[2:3], v[2:3], 0, s[88:89]
	s_waitcnt vmcnt(30)
	v_fmac_f32_e32 v6, v124, v140
	s_waitcnt vmcnt(28)
	v_fmac_f32_e32 v6, v125, v141
	s_waitcnt vmcnt(26)
	v_fmac_f32_e32 v6, v126, v142
	s_waitcnt vmcnt(24)
	v_fmac_f32_e32 v6, v127, v143
	s_waitcnt vmcnt(22)
	v_fmac_f32_e32 v6, v128, v144
	s_waitcnt vmcnt(20)
	v_fmac_f32_e32 v6, v129, v145
	s_waitcnt vmcnt(18)
	v_fmac_f32_e32 v6, v130, v146
	s_waitcnt vmcnt(16)
	v_fmac_f32_e32 v6, v131, v147
	s_waitcnt vmcnt(14)
	v_fmac_f32_e32 v6, v132, v148
	s_waitcnt vmcnt(12)
	v_fmac_f32_e32 v6, v133, v149
	s_waitcnt vmcnt(10)
	v_fmac_f32_e32 v6, v134, v150
	s_waitcnt vmcnt(8)
	v_fmac_f32_e32 v6, v135, v151
	s_waitcnt vmcnt(6)
	v_fmac_f32_e32 v6, v136, v152
	s_waitcnt vmcnt(4)
	v_fmac_f32_e32 v6, v137, v153
	s_waitcnt vmcnt(2)
	v_fmac_f32_e32 v6, v138, v154
	s_waitcnt vmcnt(0)
	v_fmac_f32_e32 v6, v139, v155
	s_add_i32 s32, s32, 1
	s_cmp_eq_u32 s32, 32
	s_cbranch_scc0 .LBB0_24
	s_or_b64 exec, exec, s[10:11]
	ds_write_b32 v13, v6
	s_waitcnt lgkmcnt(0)
	s_barrier
	s_and_saveexec_b64 s[10:11], s[4:5]
	s_cbranch_execz .LBB0_27
	ds_read2st64_b32 v[2:3], v13 offset1:1
	ds_read2st64_b32 v[4:5], v13 offset0:2 offset1:3
	ds_read2st64_b32 v[6:7], v13 offset0:4 offset1:5
	ds_read2st64_b32 v[8:9], v13 offset0:6 offset1:7
	s_lshl_b32 s12, s87, 6
	s_lshl_b32 s1, s1, 6
	s_and_b32 s12, s12, 0xc0
	s_waitcnt lgkmcnt(3)
	v_add_f32_e32 v2, 0, v2
	v_add_f32_e32 v2, v2, v3
	s_waitcnt lgkmcnt(2)
	v_add_f32_e32 v2, v2, v4
	v_add_f32_e32 v2, v2, v5
	s_waitcnt lgkmcnt(1)
	v_add_f32_e32 v2, v2, v6
	v_add_f32_e32 v2, v2, v7
	s_and_b32 s1, s1, 0x7fffff00
	s_waitcnt lgkmcnt(0)
	v_add_f32_e32 v2, v2, v8
	s_or_b32 s1, s1, s12
	v_add_f32_e32 v4, v2, v9
	v_add_u32_e32 v2, s1, v10
	v_ashrrev_i32_e32 v3, 31, v2
	v_lshl_add_u64 v[2:3], v[2:3], 2, s[26:27]
	global_store_dword v[2:3], v4, off

; DI float silu_f(float x) { return x * __builtin_amdgcn_rcpf(1.f + ex2(-LOG2E * x)); }
; DI void phase_prep(const Params& p, char* smem, int tid) {
;     ...
;     } else if (it < O_CV) {
;       int col0 = (it - O_MOD) * 64;
;       float* sc = (float*)smem;
;       float* red = (float*)(smem + 32768);
;       __syncthreads();
;       for (int i = tid; i < NB * DM; i += NTHR) sc[i] = silu_f(p.c[i]);
;       __syncthreads();
;       int col = tid & 63, kg = tid >> 6;
.LBB0_32:
	s_mov_b64 s[16:17], 0x800
	global_load_dword v124, v[2:3], off
	v_lshl_add_u64 v[2:3], v[2:3], 0, s[16:17]
	global_load_dword v125, v[2:3], off
	v_lshl_add_u64 v[2:3], v[2:3], 0, s[16:17]
	global_load_dword v126, v[2:3], off
	v_lshl_add_u64 v[2:3], v[2:3], 0, s[16:17]
	global_load_dword v127, v[2:3], off
	v_lshl_add_u64 v[2:3], v[2:3], 0, s[16:17]
	global_load_dword v128, v[2:3], off
	v_lshl_add_u64 v[2:3], v[2:3], 0, s[16:17]
	global_load_dword v129, v[2:3], off
	v_lshl_add_u64 v[2:3], v[2:3], 0, s[16:17]
	global_load_dword v130, v[2:3], off
	v_lshl_add_u64 v[2:3], v[2:3], 0, s[16:17]
	global_load_dword v131, v[2:3], off
	v_lshl_add_u64 v[2:3], v[2:3], 0, s[16:17]
	global_load_dword v132, v[2:3], off
	v_lshl_add_u64 v[2:3], v[2:3], 0, s[16:17]
	global_load_dword v133, v[2:3], off
	v_lshl_add_u64 v[2:3], v[2:3], 0, s[16:17]
	global_load_dword v134, v[2:3], off
	v_lshl_add_u64 v[2:3], v[2:3], 0, s[16:17]
	global_load_dword v135, v[2:3], off
	v_lshl_add_u64 v[2:3], v[2:3], 0, s[16:17]
	global_load_dword v136, v[2:3], off
	v_lshl_add_u64 v[2:3], v[2:3], 0, s[16:17]
	global_load_dword v137, v[2:3], off
	v_lshl_add_u64 v[2:3], v[2:3], 0, s[16:17]
	global_load_dword v138, v[2:3], off
	v_lshl_add_u64 v[2:3], v[2:3], 0, s[16:17]
	global_load_dword v139, v[2:3], off
	v_lshl_add_u64 v[2:3], v[2:3], 0, s[16:17]
	s_waitcnt vmcnt(15)
	v_mul_f32_e32 v7, 0xbfb8aa3b, v124
	v_exp_f32_e32 v7, v7
	s_nop 0
	v_add_f32_e32 v7, 1.0, v7
	v_rcp_f32_e32 v7, v7
	s_nop 0
	v_mul_f32_e32 v6, v124, v7
	ds_write_b32 v4, v6
	s_waitcnt vmcnt(14)
	v_mul_f32_e32 v7, 0xbfb8aa3b, v125
	v_exp_f32_e32 v7, v7
	s_nop 0
	v_add_f32_e32 v7, 1.0, v7
	v_rcp_f32_e32 v7, v7
	s_nop 0
	v_mul_f32_e32 v6, v125, v7
	ds_write_b32 v4, v6 offset:2048
	s_waitcnt vmcnt(13)
	v_mul_f32_e32 v7, 0xbfb8aa3b, v126
	v_exp_f32_e32 v7, v7
	s_nop 0
	v_add_f32_e32 v7, 1.0, v7
	v_rcp_f32_e32 v7, v7
	s_nop 0
	v_mul_f32_e32 v6, v126, v7
	ds_write_b32 v4, v6 offset:4096
	s_waitcnt vmcnt(12)
	v_mul_f32_e32 v7, 0xbfb8aa3b, v127
	v_exp_f32_e32 v7, v7
	s_nop 0
	v_add_f32_e32 v7, 1.0, v7
	v_rcp_f32_e32 v7, v7
	s_nop 0
	v_mul_f32_e32 v6, v127, v7
	ds_write_b32 v4, v6 offset:6144
	s_waitcnt vmcnt(11)
	v_mul_f32_e32 v7, 0xbfb8aa3b, v128
	v_exp_f32_e32 v7, v7
	s_nop 0
	v_add_f32_e32 v7, 1.0, v7
	v_rcp_f32_e32 v7, v7
	s_nop 0
	v_mul_f32_e32 v6, v128, v7
	ds_write_b32 v4, v6 offset:8192
	s_waitcnt vmcnt(10)
	v_mul_f32_e32 v7, 0xbfb8aa3b, v129
	v_exp_f32_e32 v7, v7
	s_nop 0
	v_add_f32_e32 v7, 1.0, v7
	v_rcp_f32_e32 v7, v7
	s_nop 0
	v_mul_f32_e32 v6, v129, v7
	ds_write_b32 v4, v6 offset:10240
	s_waitcnt vmcnt(9)
	v_mul_f32_e32 v7, 0xbfb8aa3b, v130
	v_exp_f32_e32 v7, v7
	s_nop 0
	v_add_f32_e32 v7, 1.0, v7
	v_rcp_f32_e32 v7, v7
	s_nop 0
	v_mul_f32_e32 v6, v130, v7
	ds_write_b32 v4, v6 offset:12288
	s_waitcnt vmcnt(8)
	v_mul_f32_e32 v7, 0xbfb8aa3b, v131
	v_exp_f32_e32 v7, v7
	s_nop 0
	v_add_f32_e32 v7, 1.0, v7
	v_rcp_f32_e32 v7, v7
	s_nop 0
	v_mul_f32_e32 v6, v131, v7
	ds_write_b32 v4, v6 offset:14336
	s_waitcnt vmcnt(7)
	v_mul_f32_e32 v7, 0xbfb8aa3b, v132
	v_exp_f32_e32 v7, v7
	s_nop 0
	v_add_f32_e32 v7, 1.0, v7
	v_rcp_f32_e32 v7, v7
	s_nop 0
	v_mul_f32_e32 v6, v132, v7
	ds_write_b32 v4, v6 offset:16384
	s_waitcnt vmcnt(6)
	v_mul_f32_e32 v7, 0xbfb8aa3b, v133
	v_exp_f32_e32 v7, v7
	s_nop 0
	v_add_f32_e32 v7, 1.0, v7
	v_rcp_f32_e32 v7, v7
	s_nop 0
	v_mul_f32_e32 v6, v133, v7
	ds_write_b32 v4, v6 offset:18432
	s_waitcnt vmcnt(5)
	v_mul_f32_e32 v7, 0xbfb8aa3b, v134
	v_exp_f32_e32 v7, v7
	s_nop 0
	v_add_f32_e32 v7, 1.0, v7
	v_rcp_f32_e32 v7, v7
	s_nop 0
	v_mul_f32_e32 v6, v134, v7
	ds_write_b32 v4, v6 offset:20480
	s_waitcnt vmcnt(4)
	v_mul_f32_e32 v7, 0xbfb8aa3b, v135
	v_exp_f32_e32 v7, v7
	s_nop 0
	v_add_f32_e32 v7, 1.0, v7
	v_rcp_f32_e32 v7, v7
	s_nop 0
	v_mul_f32_e32 v6, v135, v7
	ds_write_b32 v4, v6 offset:22528
	s_waitcnt vmcnt(3)
	v_mul_f32_e32 v7, 0xbfb8aa3b, v136
	v_exp_f32_e32 v7, v7
	s_nop 0
	v_add_f32_e32 v7, 1.0, v7
	v_rcp_f32_e32 v7, v7
	s_nop 0
	v_mul_f32_e32 v6, v136, v7
	ds_write_b32 v4, v6 offset:24576
	s_waitcnt vmcnt(2)
	v_mul_f32_e32 v7, 0xbfb8aa3b, v137
	v_exp_f32_e32 v7, v7
	s_nop 0
	v_add_f32_e32 v7, 1.0, v7
	v_rcp_f32_e32 v7, v7
	s_nop 0
	v_mul_f32_e32 v6, v137, v7
	ds_write_b32 v4, v6 offset:26624
	s_waitcnt vmcnt(1)
	v_mul_f32_e32 v7, 0xbfb8aa3b, v138
	v_exp_f32_e32 v7, v7
	s_nop 0
	v_add_f32_e32 v7, 1.0, v7
	v_rcp_f32_e32 v7, v7
	s_nop 0
	v_mul_f32_e32 v6, v138, v7
	ds_write_b32 v4, v6 offset:28672
	s_waitcnt vmcnt(0)
	v_mul_f32_e32 v7, 0xbfb8aa3b, v139
	v_exp_f32_e32 v7, v7
	s_nop 0
	v_add_f32_e32 v7, 1.0, v7
	v_rcp_f32_e32 v7, v7
	s_nop 0
	v_mul_f32_e32 v6, v139, v7
	ds_write_b32 v4, v6 offset:30720
.LBB0_33:
	s_or_b64 exec, exec, s[10:11]
	s_mov_b32 s1, s34
	v_mov_b32_e32 v4, 0
	v_lshl_add_u64 v[2:3], s[0:1], 2, v[34:35]
	s_mov_b64 s[10:11], 0
	v_mov_b32_e32 v8, v17
	v_mov_b32_e32 v5, v4
	v_mov_b32_e32 v6, v4
	v_mov_b32_e32 v7, v4
	s_waitcnt lgkmcnt(0)
	s_barrier
	s_mov_b64 s[88:89], 0x6000
	s_mov_b32 s32, 0
; DI void phase_prep(const Params& p, char* smem, int tid) {
;     ...
;       int col = tid & 63, kg = tid >> 6;
;       float a0 = 0, a1 = 0, a2 = 0, a3 = 0;
;       for (int k = kg * 256; k < kg * 256 + 256; ++k) {
;         float w = p.w_ada[(size_t)k * 6144 + col0 + col];
;         a0 += sc[k] * w; a1 += sc[DM + k] * w; a2 += sc[2 * DM + k] * w; a3 += sc[3 * DM + k] * w;
;       }
.LBB0_34:
	global_load_dword v124, v[2:3], off
	v_lshl_add_u64 v[2:3], v[2:3], 0, s[88:89]
	global_load_dword v126, v[2:3], off
	v_lshl_add_u64 v[2:3], v[2:3], 0, s[88:89]
	global_load_dword v128, v[2:3], off
	v_lshl_add_u64 v[2:3], v[2:3], 0, s[88:89]
	global_load_dword v130, v[2:3], off
	v_lshl_add_u64 v[2:3], v[2:3], 0, s[88:89]
	global_load_dword v132, v[2:3], off
	v_lshl_add_u64 v[2:3], v[2:3], 0, s[88:89]
	global_load_dword v134, v[2:3], off
	v_lshl_add_u64 v[2:3], v[2:3], 0, s[88:89]
	global_load_dword v136, v[2:3], off
	v_lshl_add_u64 v[2:3], v[2:3], 0, s[88:89]
	global_load_dword v138, v[2:3], off
	v_lshl_add_u64 v[2:3], v[2:3], 0, s[88:89]
	global_load_dword v140, v[2:3], off
	v_lshl_add_u64 v[2:3], v[2:3], 0, s[88:89]
	global_load_dword v142, v[2:3], off
	v_lshl_add_u64 v[2:3], v[2:3], 0, s[88:89]
	global_load_dword v144, v[2:3], off
	v_lshl_add_u64 v[2:3], v[2:3], 0, s[88:89]
	global_load_dword v146, v[2:3], off
	v_lshl_add_u64 v[2:3], v[2:3], 0, s[88:89]
	global_load_dword v148, v[2:3], off
	v_lshl_add_u64 v[2:3], v[2:3], 0, s[88:89]
	global_load_dword v150, v[2:3], off
	v_lshl_add_u64 v[2:3], v[2:3], 0, s[88:89]
	global_load_dword v152, v[2:3], off
	v_lshl_add_u64 v[2:3], v[2:3], 0, s[88:89]
	global_load_dword v154, v[2:3], off
	v_lshl_add_u64 v[2:3], v[2:3], 0, s[88:89]
	global_load_dword v156, v[2:3], off
	v_lshl_add_u64 v[2:3], v[2:3], 0, s[88:89]
	global_load_dword v158, v[2:3], off
	v_lshl_add_u64 v[2:3], v[2:3], 0, s[88:89]
	global_load_dword v160, v[2:3], off
	v_lshl_add_u64 v[2:3], v[2:3], 0, s[88:89]
	global_load_dword v162, v[2:3], off
	v_lshl_add_u64 v[2:3], v[2:3], 0, s[88:89]
	global_load_dword v164, v[2:3], off
	v_lshl_add_u64 v[2:3], v[2:3], 0, s[88:89]
	global_load_dword v166, v[2:3], off
	v_lshl_add_u64 v[2:3], v[2:3], 0, s[88:89]
	global_load_dword v168, v[2:3], off
	v_lshl_add_u64 v[2:3], v[2:3], 0, s[88:89]
	global_load_dword v170, v[2:3], off
	v_lshl_add_u64 v[2:3], v[2:3], 0, s[88:89]
	global_load_dword v172, v[2:3], off
	v_lshl_add_u64 v[2:3], v[2:3], 0, s[88:89]
	global_load_dword v174, v[2:3], off
	v_lshl_add_u64 v[2:3], v[2:3], 0, s[88:89]
	global_load_dword v176, v[2:3], off
	v_lshl_add_u64 v[2:3], v[2:3], 0, s[88:89]
	global_load_dword v178, v[2:3], off
	v_lshl_add_u64 v[2:3], v[2:3], 0, s[88:89]
	global_load_dword v180, v[2:3], off
	v_lshl_add_u64 v[2:3], v[2:3], 0, s[88:89]
	global_load_dword v182, v[2:3], off
	v_lshl_add_u64 v[2:3], v[2:3], 0, s[88:89]
	global_load_dword v184, v[2:3], off
	v_lshl_add_u64 v[2:3], v[2:3], 0, s[88:89]
	global_load_dword v186, v[2:3], off
	v_lshl_add_u64 v[2:3], v[2:3], 0, s[88:89]
	ds_read_b128 v[52:55], v8
	ds_read_b128 v[56:59], v8 offset:8192
	ds_read_b128 v[60:63], v8 offset:16384
	ds_read_b128 v[64:67], v8 offset:24576
	v_add_u32_e32 v8, 16, v8
	s_waitcnt lgkmcnt(3)
	v_mov_b32_e32 v74, v52
	s_waitcnt lgkmcnt(2)
	v_mov_b32_e32 v75, v56
	s_waitcnt lgkmcnt(1)
	v_mov_b32_e32 v76, v60
	s_waitcnt lgkmcnt(0)
	v_mov_b32_e32 v77, v64
	v_mov_b32_e32 v56, v53
	v_mov_b32_e32 v64, v61
	v_mov_b32_e32 v52, v54
	v_mov_b32_e32 v53, v58
	v_mov_b32_e32 v60, v62
	v_mov_b32_e32 v61, v66
	v_mov_b32_e32 v58, v55
	v_mov_b32_e32 v66, v63
	s_waitcnt vmcnt(31)
	v_pk_fma_f32 v[4:5], v[124:125], v[74:75], v[4:5] op_sel_hi:[0,1,1]
	v_pk_fma_f32 v[6:7], v[124:125], v[76:77], v[6:7] op_sel_hi:[0,1,1]
	s_waitcnt vmcnt(30)
	v_pk_fma_f32 v[4:5], v[126:127], v[56:57], v[4:5] op_sel_hi:[0,1,1]
	v_pk_fma_f32 v[6:7], v[126:127], v[64:65], v[6:7] op_sel_hi:[0,1,1]
	s_waitcnt vmcnt(29)
	v_pk_fma_f32 v[4:5], v[128:129], v[52:53], v[4:5] op_sel_hi:[0,1,1]
	v_pk_fma_f32 v[6:7], v[128:129], v[60:61], v[6:7] op_sel_hi:[0,1,1]
	s_waitcnt vmcnt(28)
	v_pk_fma_f32 v[4:5], v[130:131], v[58:59], v[4:5] op_sel_hi:[0,1,1]
	v_pk_fma_f32 v[6:7], v[130:131], v[66:67], v[6:7] op_sel_hi:[0,1,1]
	ds_read_b128 v[52:55], v8
	ds_read_b128 v[56:59], v8 offset:8192
	ds_read_b128 v[60:63], v8 offset:16384
	ds_read_b128 v[64:67], v8 offset:24576
	v_add_u32_e32 v8, 16, v8
	s_waitcnt lgkmcnt(3)
	v_mov_b32_e32 v74, v52
	s_waitcnt lgkmcnt(2)
	v_mov_b32_e32 v75, v56
	s_waitcnt lgkmcnt(1)
	v_mov_b32_e32 v76, v60
	s_waitcnt lgkmcnt(0)
	v_mov_b32_e32 v77, v64
	v_mov_b32_e32 v56, v53
	v_mov_b32_e32 v64, v61
	v_mov_b32_e32 v52, v54
	v_mov_b32_e32 v53, v58
	v_mov_b32_e32 v60, v62
	v_mov_b32_e32 v61, v66
	v_mov_b32_e32 v58, v55
	v_mov_b32_e32 v66, v63
	s_waitcnt vmcnt(27)
	v_pk_fma_f32 v[4:5], v[132:133], v[74:75], v[4:5] op_sel_hi:[0,1,1]
	v_pk_fma_f32 v[6:7], v[132:133], v[76:77], v[6:7] op_sel_hi:[0,1,1]
	s_waitcnt vmcnt(26)
	v_pk_fma_f32 v[4:5], v[134:135], v[56:57], v[4:5] op_sel_hi:[0,1,1]
	v_pk_fma_f32 v[6:7], v[134:135], v[64:65], v[6:7] op_sel_hi:[0,1,1]
	s_waitcnt vmcnt(25)
	v_pk_fma_f32 v[4:5], v[136:137], v[52:53], v[4:5] op_sel_hi:[0,1,1]
	v_pk_fma_f32 v[6:7], v[136:137], v[60:61], v[6:7] op_sel_hi:[0,1,1]
	s_waitcnt vmcnt(24)
	v_pk_fma_f32 v[4:5], v[138:139], v[58:59], v[4:5] op_sel_hi:[0,1,1]
	v_pk_fma_f32 v[6:7], v[138:139], v[66:67], v[6:7] op_sel_hi:[0,1,1]
	ds_read_b128 v[52:55], v8
	ds_read_b128 v[56:59], v8 offset:8192
	ds_read_b128 v[60:63], v8 offset:16384
	ds_read_b128 v[64:67], v8 offset:24576
	v_add_u32_e32 v8, 16, v8
	s_waitcnt lgkmcnt(3)
	v_mov_b32_e32 v74, v52
	s_waitcnt lgkmcnt(2)
	v_mov_b32_e32 v75, v56
	s_waitcnt lgkmcnt(1)
	v_mov_b32_e32 v76, v60
	s_waitcnt lgkmcnt(0)
	v_mov_b32_e32 v77, v64
	v_mov_b32_e32 v56, v53
	v_mov_b32_e32 v64, v61
	v_mov_b32_e32 v52, v54
	v_mov_b32_e32 v53, v58
	v_mov_b32_e32 v60, v62
	v_mov_b32_e32 v61, v66
	v_mov_b32_e32 v58, v55
	v_mov_b32_e32 v66, v63
	s_waitcnt vmcnt(23)
	v_pk_fma_f32 v[4:5], v[140:141], v[74:75], v[4:5] op_sel_hi:[0,1,1]
	v_pk_fma_f32 v[6:7], v[140:141], v[76:77], v[6:7] op_sel_hi:[0,1,1]
	s_waitcnt vmcnt(22)
; DI void phase_prep(const Params& p, char* smem, int tid) {
;     ...
;       int col = tid & 63, kg = tid >> 6;
;       float a0 = 0, a1 = 0, a2 = 0, a3 = 0;
;       for (int k = kg * 256; k < kg * 256 + 256; ++k) {
;         float w = p.w_ada[(size_t)k * 6144 + col0 + col];
;         a0 += sc[k] * w; a1 += sc[DM + k] * w; a2 += sc[2 * DM + k] * w; a3 += sc[3 * DM + k] * w;
;       }
	v_pk_fma_f32 v[4:5], v[142:143], v[56:57], v[4:5] op_sel_hi:[0,1,1]
	v_pk_fma_f32 v[6:7], v[142:143], v[64:65], v[6:7] op_sel_hi:[0,1,1]
	s_waitcnt vmcnt(21)
	v_pk_fma_f32 v[4:5], v[144:145], v[52:53], v[4:5] op_sel_hi:[0,1,1]
	v_pk_fma_f32 v[6:7], v[144:145], v[60:61], v[6:7] op_sel_hi:[0,1,1]
	s_waitcnt vmcnt(20)
	v_pk_fma_f32 v[4:5], v[146:147], v[58:59], v[4:5] op_sel_hi:[0,1,1]
	v_pk_fma_f32 v[6:7], v[146:147], v[66:67], v[6:7] op_sel_hi:[0,1,1]
	ds_read_b128 v[52:55], v8
	ds_read_b128 v[56:59], v8 offset:8192
	ds_read_b128 v[60:63], v8 offset:16384
	ds_read_b128 v[64:67], v8 offset:24576
	v_add_u32_e32 v8, 16, v8
	s_waitcnt lgkmcnt(3)
	v_mov_b32_e32 v74, v52
	s_waitcnt lgkmcnt(2)
	v_mov_b32_e32 v75, v56
	s_waitcnt lgkmcnt(1)
	v_mov_b32_e32 v76, v60
	s_waitcnt lgkmcnt(0)
	v_mov_b32_e32 v77, v64
	v_mov_b32_e32 v56, v53
	v_mov_b32_e32 v64, v61
	v_mov_b32_e32 v52, v54
	v_mov_b32_e32 v53, v58
	v_mov_b32_e32 v60, v62
	v_mov_b32_e32 v61, v66
	v_mov_b32_e32 v58, v55
	v_mov_b32_e32 v66, v63
	s_waitcnt vmcnt(19)
	v_pk_fma_f32 v[4:5], v[148:149], v[74:75], v[4:5] op_sel_hi:[0,1,1]
	v_pk_fma_f32 v[6:7], v[148:149], v[76:77], v[6:7] op_sel_hi:[0,1,1]
	s_waitcnt vmcnt(18)
	v_pk_fma_f32 v[4:5], v[150:151], v[56:57], v[4:5] op_sel_hi:[0,1,1]
	v_pk_fma_f32 v[6:7], v[150:151], v[64:65], v[6:7] op_sel_hi:[0,1,1]
	s_waitcnt vmcnt(17)
	v_pk_fma_f32 v[4:5], v[152:153], v[52:53], v[4:5] op_sel_hi:[0,1,1]
	v_pk_fma_f32 v[6:7], v[152:153], v[60:61], v[6:7] op_sel_hi:[0,1,1]
	s_waitcnt vmcnt(16)
	v_pk_fma_f32 v[4:5], v[154:155], v[58:59], v[4:5] op_sel_hi:[0,1,1]
	v_pk_fma_f32 v[6:7], v[154:155], v[66:67], v[6:7] op_sel_hi:[0,1,1]
	ds_read_b128 v[52:55], v8
	ds_read_b128 v[56:59], v8 offset:8192
	ds_read_b128 v[60:63], v8 offset:16384
	ds_read_b128 v[64:67], v8 offset:24576
	v_add_u32_e32 v8, 16, v8
	s_waitcnt lgkmcnt(3)
	v_mov_b32_e32 v74, v52
	s_waitcnt lgkmcnt(2)
	v_mov_b32_e32 v75, v56
	s_waitcnt lgkmcnt(1)
	v_mov_b32_e32 v76, v60
	s_waitcnt lgkmcnt(0)
	v_mov_b32_e32 v77, v64
	v_mov_b32_e32 v56, v53
	v_mov_b32_e32 v64, v61
	v_mov_b32_e32 v52, v54
	v_mov_b32_e32 v53, v58
	v_mov_b32_e32 v60, v62
	v_mov_b32_e32 v61, v66
	v_mov_b32_e32 v58, v55
	v_mov_b32_e32 v66, v63
	s_waitcnt vmcnt(15)
	v_pk_fma_f32 v[4:5], v[156:157], v[74:75], v[4:5] op_sel_hi:[0,1,1]
	v_pk_fma_f32 v[6:7], v[156:157], v[76:77], v[6:7] op_sel_hi:[0,1,1]
	s_waitcnt vmcnt(14)
	v_pk_fma_f32 v[4:5], v[158:159], v[56:57], v[4:5] op_sel_hi:[0,1,1]
	v_pk_fma_f32 v[6:7], v[158:159], v[64:65], v[6:7] op_sel_hi:[0,1,1]
	s_waitcnt vmcnt(13)
	v_pk_fma_f32 v[4:5], v[160:161], v[52:53], v[4:5] op_sel_hi:[0,1,1]
	v_pk_fma_f32 v[6:7], v[160:161], v[60:61], v[6:7] op_sel_hi:[0,1,1]
	s_waitcnt vmcnt(12)
	v_pk_fma_f32 v[4:5], v[162:163], v[58:59], v[4:5] op_sel_hi:[0,1,1]
	v_pk_fma_f32 v[6:7], v[162:163], v[66:67], v[6:7] op_sel_hi:[0,1,1]
	ds_read_b128 v[52:55], v8
	ds_read_b128 v[56:59], v8 offset:8192
	ds_read_b128 v[60:63], v8 offset:16384
	ds_read_b128 v[64:67], v8 offset:24576
	v_add_u32_e32 v8, 16, v8
	s_waitcnt lgkmcnt(3)
	v_mov_b32_e32 v74, v52
	s_waitcnt lgkmcnt(2)
	v_mov_b32_e32 v75, v56
	s_waitcnt lgkmcnt(1)
	v_mov_b32_e32 v76, v60
	s_waitcnt lgkmcnt(0)
	v_mov_b32_e32 v77, v64
	v_mov_b32_e32 v56, v53
	v_mov_b32_e32 v64, v61
	v_mov_b32_e32 v52, v54
	v_mov_b32_e32 v53, v58
	v_mov_b32_e32 v60, v62
	v_mov_b32_e32 v61, v66
	v_mov_b32_e32 v58, v55
	v_mov_b32_e32 v66, v63
	s_waitcnt vmcnt(11)
	v_pk_fma_f32 v[4:5], v[164:165], v[74:75], v[4:5] op_sel_hi:[0,1,1]
	v_pk_fma_f32 v[6:7], v[164:165], v[76:77], v[6:7] op_sel_hi:[0,1,1]
	s_waitcnt vmcnt(10)
	v_pk_fma_f32 v[4:5], v[166:167], v[56:57], v[4:5] op_sel_hi:[0,1,1]
	v_pk_fma_f32 v[6:7], v[166:167], v[64:65], v[6:7] op_sel_hi:[0,1,1]
	s_waitcnt vmcnt(9)
	v_pk_fma_f32 v[4:5], v[168:169], v[52:53], v[4:5] op_sel_hi:[0,1,1]
	v_pk_fma_f32 v[6:7], v[168:169], v[60:61], v[6:7] op_sel_hi:[0,1,1]
	s_waitcnt vmcnt(8)
	v_pk_fma_f32 v[4:5], v[170:171], v[58:59], v[4:5] op_sel_hi:[0,1,1]
	v_pk_fma_f32 v[6:7], v[170:171], v[66:67], v[6:7] op_sel_hi:[0,1,1]
	ds_read_b128 v[52:55], v8
	ds_read_b128 v[56:59], v8 offset:8192
	ds_read_b128 v[60:63], v8 offset:16384
	ds_read_b128 v[64:67], v8 offset:24576
	v_add_u32_e32 v8, 16, v8
	s_waitcnt lgkmcnt(3)
	v_mov_b32_e32 v74, v52
	s_waitcnt lgkmcnt(2)
	v_mov_b32_e32 v75, v56
	s_waitcnt lgkmcnt(1)
	v_mov_b32_e32 v76, v60
	s_waitcnt lgkmcnt(0)
	v_mov_b32_e32 v77, v64
	v_mov_b32_e32 v56, v53
	v_mov_b32_e32 v64, v61
	v_mov_b32_e32 v52, v54
	v_mov_b32_e32 v53, v58
	v_mov_b32_e32 v60, v62
	v_mov_b32_e32 v61, v66
	v_mov_b32_e32 v58, v55
	v_mov_b32_e32 v66, v63
	s_waitcnt vmcnt(7)
	v_pk_fma_f32 v[4:5], v[172:173], v[74:75], v[4:5] op_sel_hi:[0,1,1]
	v_pk_fma_f32 v[6:7], v[172:173], v[76:77], v[6:7] op_sel_hi:[0,1,1]
	s_waitcnt vmcnt(6)
	v_pk_fma_f32 v[4:5], v[174:175], v[56:57], v[4:5] op_sel_hi:[0,1,1]
	v_pk_fma_f32 v[6:7], v[174:175], v[64:65], v[6:7] op_sel_hi:[0,1,1]
	s_waitcnt vmcnt(5)
	v_pk_fma_f32 v[4:5], v[176:177], v[52:53], v[4:5] op_sel_hi:[0,1,1]
	v_pk_fma_f32 v[6:7], v[176:177], v[60:61], v[6:7] op_sel_hi:[0,1,1]
	s_waitcnt vmcnt(4)
	v_pk_fma_f32 v[4:5], v[178:179], v[58:59], v[4:5] op_sel_hi:[0,1,1]
	v_pk_fma_f32 v[6:7], v[178:179], v[66:67], v[6:7] op_sel_hi:[0,1,1]
	ds_read_b128 v[52:55], v8
	ds_read_b128 v[56:59], v8 offset:8192
	ds_read_b128 v[60:63], v8 offset:16384
	ds_read_b128 v[64:67], v8 offset:24576
	v_add_u32_e32 v8, 16, v8
	s_waitcnt lgkmcnt(3)
	v_mov_b32_e32 v74, v52
	s_waitcnt lgkmcnt(2)
	v_mov_b32_e32 v75, v56
	s_waitcnt lgkmcnt(1)
	v_mov_b32_e32 v76, v60
	s_waitcnt lgkmcnt(0)
	v_mov_b32_e32 v77, v64
	v_mov_b32_e32 v56, v53
	v_mov_b32_e32 v64, v61
	v_mov_b32_e32 v52, v54
	v_mov_b32_e32 v53, v58
	v_mov_b32_e32 v60, v62
	v_mov_b32_e32 v61, v66
	v_mov_b32_e32 v58, v55
	v_mov_b32_e32 v66, v63
	s_waitcnt vmcnt(3)
	v_pk_fma_f32 v[4:5], v[180:181], v[74:75], v[4:5] op_sel_hi:[0,1,1]
	v_pk_fma_f32 v[6:7], v[180:181], v[76:77], v[6:7] op_sel_hi:[0,1,1]
	s_waitcnt vmcnt(2)
	v_pk_fma_f32 v[4:5], v[182:183], v[56:57], v[4:5] op_sel_hi:[0,1,1]
	v_pk_fma_f32 v[6:7], v[182:183], v[64:65], v[6:7] op_sel_hi:[0,1,1]
	s_waitcnt vmcnt(1)
	v_pk_fma_f32 v[4:5], v[184:185], v[52:53], v[4:5] op_sel_hi:[0,1,1]
	v_pk_fma_f32 v[6:7], v[184:185], v[60:61], v[6:7] op_sel_hi:[0,1,1]
	s_waitcnt vmcnt(0)
	v_pk_fma_f32 v[4:5], v[186:187], v[58:59], v[4:5] op_sel_hi:[0,1,1]
	v_pk_fma_f32 v[6:7], v[186:187], v[66:67], v[6:7] op_sel_hi:[0,1,1]
	s_add_i32 s32, s32, 1
	s_cmp_eq_u32 s32, 8
	s_cbranch_scc0 .LBB0_34
; DI void phase_prep(const Params& p, char* smem, int tid) {
;     ...
;       red[(kg * 4 + 0) * 64 + col] = a0; red[(kg * 4 + 1) * 64 + col] = a1;
;       red[(kg * 4 + 2) * 64 + col] = a2; red[(kg * 4 + 3) * 64 + col] = a3;
;       __syncthreads();
;       if (tid < 256) {
;         int b = tid >> 6, cc = tid & 63; float s = 0;
; #pragma unroll
;         for (int g = 0; g < 8; ++g) s += red[(g * 4 + b) * 64 + cc];
;         p.mod[b * 6144 + col0 + cc] = s + p.b_ada[col0 + cc];
;       }
	ds_write2st64_b32 v36, v4, v5 offset0:128 offset1:129
	ds_write2st64_b32 v36, v6, v7 offset0:130 offset1:131
	s_waitcnt lgkmcnt(0)
	s_barrier
	s_and_saveexec_b64 s[10:11], s[14:15]
	s_cbranch_execz .LBB0_37
	s_load_dwordx2 s[12:13], s[92:93], 0x18
	s_lshl_b32 s1, s87, 6
	s_add_i32 s1, s1, 0xfff79c00
	v_or_b32_e32 v14, s1, v1
	v_add_u32_e32 v52, s1, v38
	s_waitcnt lgkmcnt(0)
	v_lshl_add_u64 v[2:3], v[14:15], 2, s[12:13]
	global_load_dword v14, v[2:3], off
	ds_read2st64_b32 v[2:3], v37 offset0:128 offset1:132
	ds_read2st64_b32 v[4:5], v37 offset0:136 offset1:140
	ds_read2st64_b32 v[6:7], v37 offset0:144 offset1:148
	ds_read2st64_b32 v[8:9], v37 offset0:152 offset1:156
	v_ashrrev_i32_e32 v53, 31, v52
	s_waitcnt lgkmcnt(3)
	v_add_f32_e32 v2, 0, v2
	v_add_f32_e32 v2, v2, v3
	s_waitcnt lgkmcnt(2)
	v_add_f32_e32 v2, v2, v4
	v_add_f32_e32 v2, v2, v5
	s_waitcnt lgkmcnt(1)
	v_add_f32_e32 v2, v2, v6
	v_add_f32_e32 v2, v2, v7
	s_waitcnt lgkmcnt(0)
	v_add_f32_e32 v2, v2, v8
	v_add_f32_e32 v2, v2, v9
	s_waitcnt vmcnt(0)
	v_add_f32_e32 v4, v2, v14
	v_lshl_add_u64 v[2:3], v[52:53], 2, s[24:25]
	global_store_dword v[2:3], v4, off

; DI void phase_h(const Params& p, int tid) {
;   const int lane = tid & 63, wid = tid >> 6;
;   for (int it = blockIdx.x; it < TT / 16; it += gridDim.x) {
; #pragma unroll 1
;     for (int rr = 0; rr < 2; ++rr) {
;       int row = it * 16 + wid * 2 + rr, b = row >> 13;
;       const float4* xr = (const float4*)(p.x + (size_t)row * DM);
;       float4 v[8]; float ss = 0;
; #pragma unroll
;       for (int i = 0; i < 8; ++i) { v[i] = xr[lane + 64 * i]; ss += v[i].x * v[i].x + v[i].y * v[i].y + v[i].z * v[i].z + v[i].w * v[i].w; }
;       ss = wave_sum(ss);
;       float rs = rsqrtf(ss * (1.f / DM) + EPSN);
;       const float4* g4 = (const float4*)p.norm_g;
;       const float4* sh4 = (const float4*)(p.mod + b * 6144);
;       const float4* sc4 = (const float4*)(p.mod + b * 6144 + DM);
; #pragma unroll
;       for (int i = 0; i < 8; ++i) {
;         int c4 = lane + 64 * i; float4 g = g4[c4], sh = sh4[c4], sc = sc4[c4];
;         float o0 = v[i].x * rs * g.x * (1.f + sc.x) + sh.x, o1 = v[i].y * rs * g.y * (1.f + sc.y) + sh.y;
;         float o2 = v[i].z * rs * g.z * (1.f + sc.z) + sh.z, o3 = v[i].w * rs * g.w * (1.f + sc.w) + sh.w;
.LBB0_70:
	s_or_b64 exec, exec, s[0:1]
	s_cmpk_lt_i32 s90, 0x800
	s_cselect_b64 s[0:1], -1, 0
	v_writelane_b32 v255, s0, 2
	v_mov_b32_e32 v0, v197
	s_cmpk_gt_i32 s90, 0x7ff
	v_writelane_b32 v255, s1, 3
	v_mbcnt_lo_u32_b32 v153, -1, 0
	s_barrier
	s_cbranch_scc1 .LBB0_75
	s_load_dwordx2 s[0:1], s[92:93], 0x0
	s_load_dwordx2 s[4:5], s[92:93], 0x20
	s_load_dwordx2 s[2:3], s[92:93], 0x168
	s_load_dwordx2 s[6:7], s[92:93], 0xd0
	v_and_b32_e32 v159, 63, v197
	v_lshlrev_b32_e32 v128, 4, v159
	v_lshlrev_b32_e32 v130, 3, v159
	v_add_u32_e32 v129, 0x1000, v128
	v_add_u32_e32 v147, 0x2000, v128
	v_add_u32_e32 v152, 0x3000, v128
	v_xor_b32_e32 v137, 32, v159
	v_xor_b32_e32 v138, 16, v159
	v_xor_b32_e32 v139, 8, v159
	v_xor_b32_e32 v140, 4, v159
	v_xor_b32_e32 v141, 2, v159
	v_xor_b32_e32 v142, 1, v159
	v_lshlrev_b32_e32 v137, 2, v137
	v_lshlrev_b32_e32 v138, 2, v138
	v_lshlrev_b32_e32 v139, 2, v139
	v_lshlrev_b32_e32 v140, 2, v140
	v_lshlrev_b32_e32 v141, 2, v141
	v_lshlrev_b32_e32 v142, 2, v142
	v_mov_b32_e32 v158, 0x358637bd
	v_lshrrev_b32_e32 v160, 6, v197
	v_lshlrev_b32_e32 v160, 1, v160
	v_lshl_add_u32 v160, s90, 4, v160
	v_lshl_add_u32 v131, v160, 13, v128
	v_add_u32_e32 v132, 0x1000, v131
	v_add_u32_e32 v133, 0x2000, v131
	v_add_u32_e32 v134, 0x3000, v131
	v_lshl_add_u32 v135, v160, 12, v130
	v_add_u32_e32 v136, 0x1000, v135
	s_lshl_b32 s8, s91, 17
	s_lshl_b32 s10, s91, 16
	s_mov_b32 s9, s90
	s_waitcnt lgkmcnt(0)
	global_load_dwordx4 v[0:3], v128, s[4:5]
	global_load_dwordx4 v[4:7], v128, s[4:5] offset:1024
	global_load_dwordx4 v[8:11], v128, s[4:5] offset:2048
	global_load_dwordx4 v[12:15], v128, s[4:5] offset:3072
	global_load_dwordx4 v[16:19], v129, s[4:5]
	global_load_dwordx4 v[20:23], v129, s[4:5] offset:1024
	global_load_dwordx4 v[24:27], v129, s[4:5] offset:2048
	global_load_dwordx4 v[28:31], v129, s[4:5] offset:3072
.Lp1_loop:
	s_lshr_b32 s4, s9, 9
	s_mul_i32 s4, s4, 0x6000
	s_add_u32 s4, s2, s4
	s_addc_u32 s5, s3, 0
	global_load_dwordx4 v[64:67], v147, s[4:5]
	global_load_dwordx4 v[68:71], v147, s[4:5] offset:1024
	global_load_dwordx4 v[72:75], v147, s[4:5] offset:2048
	global_load_dwordx4 v[76:79], v147, s[4:5] offset:3072
	global_load_dwordx4 v[80:83], v152, s[4:5]
	global_load_dwordx4 v[84:87], v152, s[4:5] offset:1024
	global_load_dwordx4 v[88:91], v152, s[4:5] offset:2048
	global_load_dwordx4 v[92:95], v152, s[4:5] offset:3072
	global_load_dwordx4 v[32:35], v128, s[4:5]
	global_load_dwordx4 v[36:39], v128, s[4:5] offset:1024
	global_load_dwordx4 v[40:43], v128, s[4:5] offset:2048
	global_load_dwordx4 v[44:47], v128, s[4:5] offset:3072
	global_load_dwordx4 v[48:51], v129, s[4:5]
	global_load_dwordx4 v[52:55], v129, s[4:5] offset:1024
	global_load_dwordx4 v[56:59], v129, s[4:5] offset:2048
	global_load_dwordx4 v[60:63], v129, s[4:5] offset:3072
	global_load_dwordx4 v[96:99], v131, s[0:1]
	global_load_dwordx4 v[100:103], v131, s[0:1] offset:1024
	global_load_dwordx4 v[104:107], v131, s[0:1] offset:2048
	global_load_dwordx4 v[108:111], v131, s[0:1] offset:3072
	global_load_dwordx4 v[112:115], v132, s[0:1]
	global_load_dwordx4 v[116:119], v132, s[0:1] offset:1024
	global_load_dwordx4 v[120:123], v132, s[0:1] offset:2048
	global_load_dwordx4 v[124:127], v132, s[0:1] offset:3072
	global_load_dwordx4 v[162:165], v133, s[0:1]
	global_load_dwordx4 v[166:169], v133, s[0:1] offset:1024
	global_load_dwordx4 v[170:173], v133, s[0:1] offset:2048
	global_load_dwordx4 v[174:177], v133, s[0:1] offset:3072
	global_load_dwordx4 v[178:181], v134, s[0:1]
	global_load_dwordx4 v[182:185], v134, s[0:1] offset:1024
	global_load_dwordx4 v[186:189], v134, s[0:1] offset:2048
	global_load_dwordx4 v[190:193], v134, s[0:1] offset:3072
	s_waitcnt vmcnt(31)
	v_pk_add_f32 v[64:65], v[64:65], 1.0 op_sel_hi:[1,0]
	v_pk_add_f32 v[66:67], v[66:67], 1.0 op_sel_hi:[1,0]
	s_waitcnt vmcnt(30)
	v_pk_add_f32 v[68:69], v[68:69], 1.0 op_sel_hi:[1,0]
	v_pk_add_f32 v[70:71], v[70:71], 1.0 op_sel_hi:[1,0]
	s_waitcnt vmcnt(29)
	v_pk_add_f32 v[72:73], v[72:73], 1.0 op_sel_hi:[1,0]
	v_pk_add_f32 v[74:75], v[74:75], 1.0 op_sel_hi:[1,0]
	s_waitcnt vmcnt(28)
	v_pk_add_f32 v[76:77], v[76:77], 1.0 op_sel_hi:[1,0]
	v_pk_add_f32 v[78:79], v[78:79], 1.0 op_sel_hi:[1,0]
	s_waitcnt vmcnt(27)
	v_pk_add_f32 v[80:81], v[80:81], 1.0 op_sel_hi:[1,0]
	v_pk_add_f32 v[82:83], v[82:83], 1.0 op_sel_hi:[1,0]
	s_waitcnt vmcnt(26)
	v_pk_add_f32 v[84:85], v[84:85], 1.0 op_sel_hi:[1,0]
	v_pk_add_f32 v[86:87], v[86:87], 1.0 op_sel_hi:[1,0]
	s_waitcnt vmcnt(25)
	v_pk_add_f32 v[88:89], v[88:89], 1.0 op_sel_hi:[1,0]
	v_pk_add_f32 v[90:91], v[90:91], 1.0 op_sel_hi:[1,0]
	s_waitcnt vmcnt(24)
	v_pk_add_f32 v[92:93], v[92:93], 1.0 op_sel_hi:[1,0]
	v_pk_add_f32 v[94:95], v[94:95], 1.0 op_sel_hi:[1,0]
	s_waitcnt vmcnt(15)
	v_pk_mul_f32 v[154:155], v[96:97], v[96:97]
	v_pk_fma_f32 v[154:155], v[98:99], v[98:99], v[154:155]
	s_waitcnt vmcnt(14)
	v_pk_fma_f32 v[154:155], v[100:101], v[100:101], v[154:155]
	v_pk_fma_f32 v[154:155], v[102:103], v[102:103], v[154:155]
	s_waitcnt vmcnt(13)
	v_pk_fma_f32 v[154:155], v[104:105], v[104:105], v[154:155]
	v_pk_fma_f32 v[154:155], v[106:107], v[106:107], v[154:155]
	s_waitcnt vmcnt(12)
	v_pk_fma_f32 v[154:155], v[108:109], v[108:109], v[154:155]
	v_pk_fma_f32 v[154:155], v[110:111], v[110:111], v[154:155]
	s_waitcnt vmcnt(11)
	v_pk_fma_f32 v[154:155], v[112:113], v[112:113], v[154:155]
	v_pk_fma_f32 v[154:155], v[114:115], v[114:115], v[154:155]
	s_waitcnt vmcnt(10)
	v_pk_fma_f32 v[154:155], v[116:117], v[116:117], v[154:155]
	v_pk_fma_f32 v[154:155], v[118:119], v[118:119], v[154:155]
	s_waitcnt vmcnt(9)
; DI unsigned pk2(float a, float b) { f32x2 v = {a, b}; bf16x2_t r = __builtin_convertvector(v, bf16x2_t); return __builtin_bit_cast(unsigned, r); }
; DI void phase_h(const Params& p, int tid) {
;     ...
;       for (int i = 0; i < 8; ++i) { v[i] = xr[lane + 64 * i]; ss += v[i].x * v[i].x + v[i].y * v[i].y + v[i].z * v[i].z + v[i].w * v[i].w; }
;       ss = wave_sum(ss);
;       float rs = rsqrtf(ss * (1.f / DM) + EPSN);
;       const float4* g4 = (const float4*)p.norm_g;
;       const float4* sh4 = (const float4*)(p.mod + b * 6144);
;       const float4* sc4 = (const float4*)(p.mod + b * 6144 + DM);
; #pragma unroll
;       for (int i = 0; i < 8; ++i) {
;         int c4 = lane + 64 * i; float4 g = g4[c4], sh = sh4[c4], sc = sc4[c4];
;         float o0 = v[i].x * rs * g.x * (1.f + sc.x) + sh.x, o1 = v[i].y * rs * g.y * (1.f + sc.y) + sh.y;
;         float o2 = v[i].z * rs * g.z * (1.f + sc.z) + sh.z, o3 = v[i].w * rs * g.w * (1.f + sc.w) + sh.w;
;         uint2 w = {pk2(o0, o1), pk2(o2, o3)};
;         *(uint2*)(p.H + (size_t)row * DM + c4 * 4) = w;
	v_pk_fma_f32 v[154:155], v[120:121], v[120:121], v[154:155]
	v_pk_fma_f32 v[154:155], v[122:123], v[122:123], v[154:155]
	s_waitcnt vmcnt(8)
	v_pk_fma_f32 v[154:155], v[124:125], v[124:125], v[154:155]
	v_pk_fma_f32 v[154:155], v[126:127], v[126:127], v[154:155]
	v_add_f32_e32 v143, v154, v155
	s_waitcnt vmcnt(7)
	v_pk_mul_f32 v[156:157], v[162:163], v[162:163]
	v_pk_fma_f32 v[156:157], v[164:165], v[164:165], v[156:157]
	s_waitcnt vmcnt(6)
	v_pk_fma_f32 v[156:157], v[166:167], v[166:167], v[156:157]
	v_pk_fma_f32 v[156:157], v[168:169], v[168:169], v[156:157]
	s_waitcnt vmcnt(5)
	v_pk_fma_f32 v[156:157], v[170:171], v[170:171], v[156:157]
	v_pk_fma_f32 v[156:157], v[172:173], v[172:173], v[156:157]
	s_waitcnt vmcnt(4)
	v_pk_fma_f32 v[156:157], v[174:175], v[174:175], v[156:157]
	v_pk_fma_f32 v[156:157], v[176:177], v[176:177], v[156:157]
	s_waitcnt vmcnt(3)
	v_pk_fma_f32 v[156:157], v[178:179], v[178:179], v[156:157]
	v_pk_fma_f32 v[156:157], v[180:181], v[180:181], v[156:157]
	s_waitcnt vmcnt(2)
	v_pk_fma_f32 v[156:157], v[182:183], v[182:183], v[156:157]
	v_pk_fma_f32 v[156:157], v[184:185], v[184:185], v[156:157]
	s_waitcnt vmcnt(1)
	v_pk_fma_f32 v[156:157], v[186:187], v[186:187], v[156:157]
	v_pk_fma_f32 v[156:157], v[188:189], v[188:189], v[156:157]
	s_waitcnt vmcnt(0)
	v_pk_fma_f32 v[156:157], v[190:191], v[190:191], v[156:157]
	v_pk_fma_f32 v[156:157], v[192:193], v[192:193], v[156:157]
	v_add_f32_e32 v144, v156, v157
	ds_bpermute_b32 v145, v137, v143
	ds_bpermute_b32 v146, v137, v144
	s_waitcnt lgkmcnt(1)
	v_add_f32_e32 v143, v143, v145
	s_waitcnt lgkmcnt(0)
	v_add_f32_e32 v144, v144, v146
	ds_bpermute_b32 v145, v138, v143
	ds_bpermute_b32 v146, v138, v144
	s_waitcnt lgkmcnt(1)
	v_add_f32_e32 v143, v143, v145
	s_waitcnt lgkmcnt(0)
	v_add_f32_e32 v144, v144, v146
	ds_bpermute_b32 v145, v139, v143
	ds_bpermute_b32 v146, v139, v144
	s_waitcnt lgkmcnt(1)
	v_add_f32_e32 v143, v143, v145
	s_waitcnt lgkmcnt(0)
	v_add_f32_e32 v144, v144, v146
	ds_bpermute_b32 v145, v140, v143
	ds_bpermute_b32 v146, v140, v144
	s_waitcnt lgkmcnt(1)
	v_add_f32_e32 v143, v143, v145
	s_waitcnt lgkmcnt(0)
	v_add_f32_e32 v144, v144, v146
	ds_bpermute_b32 v145, v141, v143
	ds_bpermute_b32 v146, v141, v144
	s_waitcnt lgkmcnt(1)
	v_add_f32_e32 v143, v143, v145
	s_waitcnt lgkmcnt(0)
	v_add_f32_e32 v144, v144, v146
	ds_bpermute_b32 v145, v142, v143
	ds_bpermute_b32 v146, v142, v144
	s_waitcnt lgkmcnt(1)
	v_add_f32_e32 v143, v143, v145
	s_waitcnt lgkmcnt(0)
	v_add_f32_e32 v144, v144, v146
	v_fmamk_f32 v143, v143, 0x3a000000, v158
	v_fmamk_f32 v144, v144, 0x3a000000, v158
	v_rsq_f32_e32 v148, v143
	v_rsq_f32_e32 v150, v144
	s_nop 0
	v_pk_mul_f32 v[96:97], v[96:97], v[148:149] op_sel_hi:[1,0]
	v_pk_mul_f32 v[98:99], v[98:99], v[148:149] op_sel_hi:[1,0]
	v_pk_mul_f32 v[96:97], v[0:1], v[96:97]
	v_pk_mul_f32 v[98:99], v[2:3], v[98:99]
	v_pk_fma_f32 v[96:97], v[64:65], v[96:97], v[32:33]
	v_pk_fma_f32 v[98:99], v[66:67], v[98:99], v[34:35]
	v_cvt_pk_bf16_f32 v96, v96, v97
	v_cvt_pk_bf16_f32 v97, v98, v99
	global_store_dwordx2 v135, v[96:97], s[6:7]
	v_pk_mul_f32 v[100:101], v[100:101], v[148:149] op_sel_hi:[1,0]
	v_pk_mul_f32 v[102:103], v[102:103], v[148:149] op_sel_hi:[1,0]
	v_pk_mul_f32 v[100:101], v[4:5], v[100:101]
	v_pk_mul_f32 v[102:103], v[6:7], v[102:103]
	v_pk_fma_f32 v[100:101], v[68:69], v[100:101], v[36:37]
	v_pk_fma_f32 v[102:103], v[70:71], v[102:103], v[38:39]
	v_cvt_pk_bf16_f32 v100, v100, v101
	v_cvt_pk_bf16_f32 v101, v102, v103
	global_store_dwordx2 v135, v[100:101], s[6:7] offset:512
	v_pk_mul_f32 v[104:105], v[104:105], v[148:149] op_sel_hi:[1,0]
	v_pk_mul_f32 v[106:107], v[106:107], v[148:149] op_sel_hi:[1,0]
	v_pk_mul_f32 v[104:105], v[8:9], v[104:105]
	v_pk_mul_f32 v[106:107], v[10:11], v[106:107]
	v_pk_fma_f32 v[104:105], v[72:73], v[104:105], v[40:41]
	v_pk_fma_f32 v[106:107], v[74:75], v[106:107], v[42:43]
	v_cvt_pk_bf16_f32 v104, v104, v105
	v_cvt_pk_bf16_f32 v105, v106, v107
	global_store_dwordx2 v135, v[104:105], s[6:7] offset:1024
	v_pk_mul_f32 v[108:109], v[108:109], v[148:149] op_sel_hi:[1,0]
	v_pk_mul_f32 v[110:111], v[110:111], v[148:149] op_sel_hi:[1,0]
	v_pk_mul_f32 v[108:109], v[12:13], v[108:109]
	v_pk_mul_f32 v[110:111], v[14:15], v[110:111]
	v_pk_fma_f32 v[108:109], v[76:77], v[108:109], v[44:45]
	v_pk_fma_f32 v[110:111], v[78:79], v[110:111], v[46:47]
	v_cvt_pk_bf16_f32 v108, v108, v109
	v_cvt_pk_bf16_f32 v109, v110, v111
	global_store_dwordx2 v135, v[108:109], s[6:7] offset:1536
	v_pk_mul_f32 v[112:113], v[112:113], v[148:149] op_sel_hi:[1,0]
	v_pk_mul_f32 v[114:115], v[114:115], v[148:149] op_sel_hi:[1,0]
	v_pk_mul_f32 v[112:113], v[16:17], v[112:113]
	v_pk_mul_f32 v[114:115], v[18:19], v[114:115]
	v_pk_fma_f32 v[112:113], v[80:81], v[112:113], v[48:49]
	v_pk_fma_f32 v[114:115], v[82:83], v[114:115], v[50:51]
	v_cvt_pk_bf16_f32 v112, v112, v113
	v_cvt_pk_bf16_f32 v113, v114, v115
	global_store_dwordx2 v135, v[112:113], s[6:7] offset:2048
	v_pk_mul_f32 v[116:117], v[116:117], v[148:149] op_sel_hi:[1,0]
	v_pk_mul_f32 v[118:119], v[118:119], v[148:149] op_sel_hi:[1,0]
	v_pk_mul_f32 v[116:117], v[20:21], v[116:117]
	v_pk_mul_f32 v[118:119], v[22:23], v[118:119]
; DI unsigned pk2(float a, float b) { f32x2 v = {a, b}; bf16x2_t r = __builtin_convertvector(v, bf16x2_t); return __builtin_bit_cast(unsigned, r); }
; DI void phase_h(const Params& p, int tid) {
;     ...
;       for (int i = 0; i < 8; ++i) {
;         int c4 = lane + 64 * i; float4 g = g4[c4], sh = sh4[c4], sc = sc4[c4];
;         float o0 = v[i].x * rs * g.x * (1.f + sc.x) + sh.x, o1 = v[i].y * rs * g.y * (1.f + sc.y) + sh.y;
;         float o2 = v[i].z * rs * g.z * (1.f + sc.z) + sh.z, o3 = v[i].w * rs * g.w * (1.f + sc.w) + sh.w;
;         uint2 w = {pk2(o0, o1), pk2(o2, o3)};
;         *(uint2*)(p.H + (size_t)row * DM + c4 * 4) = w;
;       }
;     }
	v_pk_fma_f32 v[116:117], v[84:85], v[116:117], v[52:53]
	v_pk_fma_f32 v[118:119], v[86:87], v[118:119], v[54:55]
	v_cvt_pk_bf16_f32 v116, v116, v117
	v_cvt_pk_bf16_f32 v117, v118, v119
	global_store_dwordx2 v135, v[116:117], s[6:7] offset:2560
	v_pk_mul_f32 v[120:121], v[120:121], v[148:149] op_sel_hi:[1,0]
	v_pk_mul_f32 v[122:123], v[122:123], v[148:149] op_sel_hi:[1,0]
	v_pk_mul_f32 v[120:121], v[24:25], v[120:121]
	v_pk_mul_f32 v[122:123], v[26:27], v[122:123]
	v_pk_fma_f32 v[120:121], v[88:89], v[120:121], v[56:57]
	v_pk_fma_f32 v[122:123], v[90:91], v[122:123], v[58:59]
	v_cvt_pk_bf16_f32 v120, v120, v121
	v_cvt_pk_bf16_f32 v121, v122, v123
	global_store_dwordx2 v135, v[120:121], s[6:7] offset:3072
	v_pk_mul_f32 v[124:125], v[124:125], v[148:149] op_sel_hi:[1,0]
	v_pk_mul_f32 v[126:127], v[126:127], v[148:149] op_sel_hi:[1,0]
	v_pk_mul_f32 v[124:125], v[28:29], v[124:125]
	v_pk_mul_f32 v[126:127], v[30:31], v[126:127]
	v_pk_fma_f32 v[124:125], v[92:93], v[124:125], v[60:61]
	v_pk_fma_f32 v[126:127], v[94:95], v[126:127], v[62:63]
	v_cvt_pk_bf16_f32 v124, v124, v125
	v_cvt_pk_bf16_f32 v125, v126, v127
	global_store_dwordx2 v135, v[124:125], s[6:7] offset:3584
	v_pk_mul_f32 v[162:163], v[162:163], v[150:151] op_sel_hi:[1,0]
	v_pk_mul_f32 v[164:165], v[164:165], v[150:151] op_sel_hi:[1,0]
	v_pk_mul_f32 v[162:163], v[0:1], v[162:163]
	v_pk_mul_f32 v[164:165], v[2:3], v[164:165]
	v_pk_fma_f32 v[162:163], v[64:65], v[162:163], v[32:33]
	v_pk_fma_f32 v[164:165], v[66:67], v[164:165], v[34:35]
	v_cvt_pk_bf16_f32 v162, v162, v163
	v_cvt_pk_bf16_f32 v163, v164, v165
	global_store_dwordx2 v136, v[162:163], s[6:7]
	v_pk_mul_f32 v[166:167], v[166:167], v[150:151] op_sel_hi:[1,0]
	v_pk_mul_f32 v[168:169], v[168:169], v[150:151] op_sel_hi:[1,0]
	v_pk_mul_f32 v[166:167], v[4:5], v[166:167]
	v_pk_mul_f32 v[168:169], v[6:7], v[168:169]
	v_pk_fma_f32 v[166:167], v[68:69], v[166:167], v[36:37]
	v_pk_fma_f32 v[168:169], v[70:71], v[168:169], v[38:39]
	v_cvt_pk_bf16_f32 v166, v166, v167
	v_cvt_pk_bf16_f32 v167, v168, v169
	global_store_dwordx2 v136, v[166:167], s[6:7] offset:512
	v_pk_mul_f32 v[170:171], v[170:171], v[150:151] op_sel_hi:[1,0]
	v_pk_mul_f32 v[172:173], v[172:173], v[150:151] op_sel_hi:[1,0]
	v_pk_mul_f32 v[170:171], v[8:9], v[170:171]
	v_pk_mul_f32 v[172:173], v[10:11], v[172:173]
	v_pk_fma_f32 v[170:171], v[72:73], v[170:171], v[40:41]
	v_pk_fma_f32 v[172:173], v[74:75], v[172:173], v[42:43]
	v_cvt_pk_bf16_f32 v170, v170, v171
	v_cvt_pk_bf16_f32 v171, v172, v173
	global_store_dwordx2 v136, v[170:171], s[6:7] offset:1024
	v_pk_mul_f32 v[174:175], v[174:175], v[150:151] op_sel_hi:[1,0]
	v_pk_mul_f32 v[176:177], v[176:177], v[150:151] op_sel_hi:[1,0]
	v_pk_mul_f32 v[174:175], v[12:13], v[174:175]
	v_pk_mul_f32 v[176:177], v[14:15], v[176:177]
	v_pk_fma_f32 v[174:175], v[76:77], v[174:175], v[44:45]
	v_pk_fma_f32 v[176:177], v[78:79], v[176:177], v[46:47]
	v_cvt_pk_bf16_f32 v174, v174, v175
	v_cvt_pk_bf16_f32 v175, v176, v177
	global_store_dwordx2 v136, v[174:175], s[6:7] offset:1536
	v_pk_mul_f32 v[178:179], v[178:179], v[150:151] op_sel_hi:[1,0]
	v_pk_mul_f32 v[180:181], v[180:181], v[150:151] op_sel_hi:[1,0]
	v_pk_mul_f32 v[178:179], v[16:17], v[178:179]
	v_pk_mul_f32 v[180:181], v[18:19], v[180:181]
	v_pk_fma_f32 v[178:179], v[80:81], v[178:179], v[48:49]
	v_pk_fma_f32 v[180:181], v[82:83], v[180:181], v[50:51]
	v_cvt_pk_bf16_f32 v178, v178, v179
	v_cvt_pk_bf16_f32 v179, v180, v181
	global_store_dwordx2 v136, v[178:179], s[6:7] offset:2048
	v_pk_mul_f32 v[182:183], v[182:183], v[150:151] op_sel_hi:[1,0]
	v_pk_mul_f32 v[184:185], v[184:185], v[150:151] op_sel_hi:[1,0]
	v_pk_mul_f32 v[182:183], v[20:21], v[182:183]
	v_pk_mul_f32 v[184:185], v[22:23], v[184:185]
	v_pk_fma_f32 v[182:183], v[84:85], v[182:183], v[52:53]
	v_pk_fma_f32 v[184:185], v[86:87], v[184:185], v[54:55]
	v_cvt_pk_bf16_f32 v182, v182, v183
	v_cvt_pk_bf16_f32 v183, v184, v185
	global_store_dwordx2 v136, v[182:183], s[6:7] offset:2560
	v_pk_mul_f32 v[186:187], v[186:187], v[150:151] op_sel_hi:[1,0]
	v_pk_mul_f32 v[188:189], v[188:189], v[150:151] op_sel_hi:[1,0]
	v_pk_mul_f32 v[186:187], v[24:25], v[186:187]
	v_pk_mul_f32 v[188:189], v[26:27], v[188:189]
	v_pk_fma_f32 v[186:187], v[88:89], v[186:187], v[56:57]
	v_pk_fma_f32 v[188:189], v[90:91], v[188:189], v[58:59]
	v_cvt_pk_bf16_f32 v186, v186, v187
	v_cvt_pk_bf16_f32 v187, v188, v189
	global_store_dwordx2 v136, v[186:187], s[6:7] offset:3072
	v_pk_mul_f32 v[190:191], v[190:191], v[150:151] op_sel_hi:[1,0]
	v_pk_mul_f32 v[192:193], v[192:193], v[150:151] op_sel_hi:[1,0]
	v_pk_mul_f32 v[190:191], v[28:29], v[190:191]
	v_pk_mul_f32 v[192:193], v[30:31], v[192:193]
	v_pk_fma_f32 v[190:191], v[92:93], v[190:191], v[60:61]
	v_pk_fma_f32 v[192:193], v[94:95], v[192:193], v[62:63]
	v_cvt_pk_bf16_f32 v190, v190, v191
	v_cvt_pk_bf16_f32 v191, v192, v193
	global_store_dwordx2 v136, v[190:191], s[6:7] offset:3584
	s_add_i32 s9, s9, s91
	v_add_u32_e32 v131, s8, v131
	v_add_u32_e32 v133, s8, v133
	v_add_u32_e32 v132, s8, v132
	v_add_u32_e32 v134, s8, v134
	v_add_u32_e32 v135, s10, v135
	v_add_u32_e32 v136, s10, v136
	s_cmpk_gt_i32 s9, 0x7ff
	s_cbranch_scc0 .Lp1_loop

; DI void diff_item(const Params& p, int b, int h, int qb, float lam, char* smem, int tid) {
;     ...
;     if (m == 0) {
; #pragma unroll
;       for (int qt = 0; qt < 2; ++qt) {
;         const float i1 = 1.f / (qt ? lb : la);
;         f32x4 ov[8];
;         float ss = 0.f;
; #pragma unroll
;         for (int dt = 0; dt < 8; ++dt) {
;           ov[dt] = (qt ? o1[dt] : o0[dt]) * i1 - X[((qg * 2 + qt) * 8 + dt) * 64 + lane];
;           ss += ov[dt][0] * ov[dt][0] + ov[dt][1] * ov[dt][1] + ov[dt][2] * ov[dt][2] + ov[dt][3] * ov[dt][3];
;         }
;         ss += __shfl_xor(ss, 16); ss += __shfl_xor(ss, 32);
;         const float rn = rsqrtf(ss * (1.f / 128.f) + EPSN) * 0.8f;
;         const size_t t = (size_t)(b * SQ + (qt ? qp1 : qp0));
; #pragma unroll
;         for (int dt = 0; dt < 8; ++dt) {
;           const int d0 = dt * 16 + quad * 4;
;           float4 g = *(const float4*)(p.diff_g + d0);
;           uint2 z = *(const uint2*)(p.Za + t * 1024 + h * 128 + d0);
.LBB0_590:
	s_or_b64 exec, exec, s[4:5]
	v_cmp_gt_u32_e32 vcc, s55, v190
	s_waitcnt lgkmcnt(0)
	s_barrier
	s_and_saveexec_b64 s[4:5], vcc
	s_xor_b64 s[4:5], exec, s[4:5]
	s_cbranch_execz .LBB0_592
	s_load_dwordx2 s[8:9], s[92:93], 0xf0
	v_mov_b32_e32 v145, v0
	v_mov_b32_e32 v146, v26
	v_mov_b32_e32 v148, v11
	v_mov_b32_e32 v149, v28
	v_and_b32_e32 v150, 63, v190
	v_lshrrev_b32_e32 v152, 4, v150
	v_lshlrev_b32_e32 v152, 2, v152
	s_lshl_b32 s0, s60, 1
	v_lshlrev_b32_e32 v153, 1, v152
	v_add_u32_e32 v153, s0, v153
	v_lshl_add_u32 v154, v203, 11, v153
	v_lshl_add_u32 v156, v201, 11, v153
	v_lshl_add_u32 v157, v203, 12, v153
	v_lshl_add_u32 v158, v201, 12, v153
	v_lshlrev_b32_e32 v178, 2, v152
	v_lshlrev_b32_e32 v218, 4, v150
	v_lshl_add_u32 v218, v205, 14, v218
	s_waitcnt lgkmcnt(0)
	global_load_dwordx4 v[160:163], v178, s[2:3]
	global_load_dwordx4 v[164:167], v178, s[2:3] offset:64
	global_load_dwordx4 v[168:171], v178, s[2:3] offset:128
	global_load_dwordx4 v[172:175], v178, s[2:3] offset:192
	global_load_dwordx4 v[96:99], v178, s[2:3] offset:256
	global_load_dwordx4 v[100:103], v178, s[2:3] offset:320
	global_load_dwordx4 v[104:107], v178, s[2:3] offset:384
	global_load_dwordx4 v[108:111], v178, s[2:3] offset:448
	global_load_dwordx2 v[234:235], v154, s[8:9]
	global_load_dwordx2 v[236:237], v154, s[8:9] offset:32
	global_load_dwordx2 v[238:239], v154, s[8:9] offset:64
	global_load_dwordx2 v[240:241], v154, s[8:9] offset:96
	global_load_dwordx2 v[242:243], v154, s[8:9] offset:128
	global_load_dwordx2 v[244:245], v154, s[8:9] offset:160
	global_load_dwordx2 v[246:247], v154, s[8:9] offset:192
	global_load_dwordx2 v[248:249], v154, s[8:9] offset:224
	global_load_dwordx2 v[250:251], v156, s[8:9]
	global_load_dwordx2 v[252:253], v156, s[8:9] offset:32
	global_load_dwordx2 v[184:185], v156, s[8:9] offset:64
	global_load_dwordx2 v[186:187], v156, s[8:9] offset:96
	global_load_dwordx2 v[188:189], v156, s[8:9] offset:128
	global_load_dwordx2 v[208:209], v156, s[8:9] offset:160
	global_load_dwordx2 v[214:215], v156, s[8:9] offset:192
	global_load_dwordx2 v[216:217], v156, s[8:9] offset:224
	ds_read_b128 v[0:3], v218 offset:0
	ds_read_b128 v[4:7], v218 offset:1024
	ds_read_b128 v[8:11], v218 offset:2048
	ds_read_b128 v[12:15], v218 offset:3072
	ds_read_b128 v[16:19], v218 offset:4096
	ds_read_b128 v[20:23], v218 offset:5120
	ds_read_b128 v[24:27], v218 offset:6144
	ds_read_b128 v[28:31], v218 offset:7168
	v_div_scale_f32 v219, s[6:7], v145, v145, 1.0
	v_rcp_f32_e32 v231, v219
	v_div_scale_f32 v232, vcc, 1.0, v145, 1.0
	v_fma_f32 v212, -v219, v231, 1.0
	v_fmac_f32_e32 v231, v212, v231
	v_mul_f32_e32 v213, v232, v231
	v_fma_f32 v212, -v219, v213, v232
	v_fmac_f32_e32 v213, v212, v231
	v_fma_f32 v212, -v219, v213, v232
	s_nop 0
	v_div_fmas_f32 v212, v212, v231, v213
	v_div_fixup_f32 v220, v212, v145, 1.0
	s_waitcnt lgkmcnt(7)
	v_pk_fma_f32 v[92:93], v[92:93], v[220:221], v[0:1] op_sel_hi:[1,0,1] neg_lo:[0,0,1] neg_hi:[0,0,1]
	v_pk_fma_f32 v[94:95], v[94:95], v[220:221], v[2:3] op_sel_hi:[1,0,1] neg_lo:[0,0,1] neg_hi:[0,0,1]
	v_pk_mul_f32 v[210:211], v[92:93], v[92:93]
	v_pk_fma_f32 v[210:211], v[94:95], v[94:95], v[210:211]
	s_waitcnt lgkmcnt(6)
	v_pk_fma_f32 v[88:89], v[88:89], v[220:221], v[4:5] op_sel_hi:[1,0,1] neg_lo:[0,0,1] neg_hi:[0,0,1]
	v_pk_fma_f32 v[90:91], v[90:91], v[220:221], v[6:7] op_sel_hi:[1,0,1] neg_lo:[0,0,1] neg_hi:[0,0,1]
	v_pk_fma_f32 v[210:211], v[88:89], v[88:89], v[210:211]
	v_pk_fma_f32 v[210:211], v[90:91], v[90:91], v[210:211]
	s_waitcnt lgkmcnt(5)
	v_pk_fma_f32 v[84:85], v[84:85], v[220:221], v[8:9] op_sel_hi:[1,0,1] neg_lo:[0,0,1] neg_hi:[0,0,1]
	v_pk_fma_f32 v[86:87], v[86:87], v[220:221], v[10:11] op_sel_hi:[1,0,1] neg_lo:[0,0,1] neg_hi:[0,0,1]
	v_pk_fma_f32 v[210:211], v[84:85], v[84:85], v[210:211]
	v_pk_fma_f32 v[210:211], v[86:87], v[86:87], v[210:211]
	s_waitcnt lgkmcnt(4)
	v_pk_fma_f32 v[80:81], v[80:81], v[220:221], v[12:13] op_sel_hi:[1,0,1] neg_lo:[0,0,1] neg_hi:[0,0,1]
	v_pk_fma_f32 v[82:83], v[82:83], v[220:221], v[14:15] op_sel_hi:[1,0,1] neg_lo:[0,0,1] neg_hi:[0,0,1]
	v_pk_fma_f32 v[210:211], v[80:81], v[80:81], v[210:211]
	v_pk_fma_f32 v[210:211], v[82:83], v[82:83], v[210:211]
	s_waitcnt lgkmcnt(3)
	v_pk_fma_f32 v[76:77], v[76:77], v[220:221], v[16:17] op_sel_hi:[1,0,1] neg_lo:[0,0,1] neg_hi:[0,0,1]
	v_pk_fma_f32 v[78:79], v[78:79], v[220:221], v[18:19] op_sel_hi:[1,0,1] neg_lo:[0,0,1] neg_hi:[0,0,1]
	v_pk_fma_f32 v[210:211], v[76:77], v[76:77], v[210:211]
	v_pk_fma_f32 v[210:211], v[78:79], v[78:79], v[210:211]
	s_waitcnt lgkmcnt(2)
	v_pk_fma_f32 v[72:73], v[72:73], v[220:221], v[20:21] op_sel_hi:[1,0,1] neg_lo:[0,0,1] neg_hi:[0,0,1]
	v_pk_fma_f32 v[74:75], v[74:75], v[220:221], v[22:23] op_sel_hi:[1,0,1] neg_lo:[0,0,1] neg_hi:[0,0,1]
	v_pk_fma_f32 v[210:211], v[72:73], v[72:73], v[210:211]
	v_pk_fma_f32 v[210:211], v[74:75], v[74:75], v[210:211]
	s_waitcnt lgkmcnt(1)
	v_pk_fma_f32 v[68:69], v[68:69], v[220:221], v[24:25] op_sel_hi:[1,0,1] neg_lo:[0,0,1] neg_hi:[0,0,1]
	v_pk_fma_f32 v[70:71], v[70:71], v[220:221], v[26:27] op_sel_hi:[1,0,1] neg_lo:[0,0,1] neg_hi:[0,0,1]
	v_pk_fma_f32 v[210:211], v[68:69], v[68:69], v[210:211]
	v_pk_fma_f32 v[210:211], v[70:71], v[70:71], v[210:211]
	s_waitcnt lgkmcnt(0)
	v_pk_fma_f32 v[64:65], v[64:65], v[220:221], v[28:29] op_sel_hi:[1,0,1] neg_lo:[0,0,1] neg_hi:[0,0,1]
	v_pk_fma_f32 v[66:67], v[66:67], v[220:221], v[30:31] op_sel_hi:[1,0,1] neg_lo:[0,0,1] neg_hi:[0,0,1]
	v_pk_fma_f32 v[210:211], v[64:65], v[64:65], v[210:211]
	v_pk_fma_f32 v[210:211], v[66:67], v[66:67], v[210:211]
	v_add_f32_e32 v212, v210, v211
	ds_bpermute_b32 v213, v148, v212
	s_waitcnt lgkmcnt(0)
; DI unsigned pk2(float a, float b) { f32x2 v = {a, b}; bf16x2_t r = __builtin_convertvector(v, bf16x2_t); return __builtin_bit_cast(unsigned, r); }
; DI float bflo(unsigned w) { return __uint_as_float(w << 16); }
; DI float bfhi(unsigned w) { return __uint_as_float(w & 0xffff0000u); }
; DI void diff_item(const Params& p, int b, int h, int qb, float lam, char* smem, int tid) {
;     ...
;         ss += __shfl_xor(ss, 16); ss += __shfl_xor(ss, 32);
;         const float rn = rsqrtf(ss * (1.f / 128.f) + EPSN) * 0.8f;
;         const size_t t = (size_t)(b * SQ + (qt ? qp1 : qp0));
; #pragma unroll
;         for (int dt = 0; dt < 8; ++dt) {
;           const int d0 = dt * 16 + quad * 4;
;           float4 g = *(const float4*)(p.diff_g + d0);
;           uint2 z = *(const uint2*)(p.Za + t * 1024 + h * 128 + d0);
;           float v0 = ov[dt][0] * rn * g.x * bflo(z.x), v1 = ov[dt][1] * rn * g.y * bfhi(z.x);
;           float v2 = ov[dt][2] * rn * g.z * bflo(z.y), v3 = ov[dt][3] * rn * g.w * bfhi(z.y);
;           uint2 w = {pk2(v0, v1), pk2(v2, v3)};
;           *(uint2*)(p.H + t * DM + h * 128 + d0) = w;
;         }
;       }
	v_add_f32_e32 v212, v212, v213
	ds_bpermute_b32 v213, v149, v212
	s_waitcnt lgkmcnt(0)
	v_add_f32_e32 v212, v212, v213
	v_fmamk_f32 v212, v212, 0x3c000000, v194
	v_rsq_f32_e32 v206, v212
	s_nop 0
	v_mul_f32_e32 v206, 0x3f4ccccd, v206
	s_waitcnt vmcnt(15)
	v_pk_mul_f32 v[92:93], v[92:93], v[206:207] op_sel_hi:[1,0]
	v_pk_mul_f32 v[94:95], v[94:95], v[206:207] op_sel_hi:[1,0]
	v_pk_mul_f32 v[92:93], v[160:161], v[92:93]
	v_pk_mul_f32 v[94:95], v[162:163], v[94:95]
	v_lshlrev_b32_e32 v0, 16, v234
	v_and_b32_e32 v1, 0xffff0000, v234
	v_lshlrev_b32_e32 v2, 16, v235
	v_and_b32_e32 v3, 0xffff0000, v235
	v_pk_mul_f32 v[92:93], v[92:93], v[0:1]
	v_pk_mul_f32 v[94:95], v[94:95], v[2:3]
	v_cvt_pk_bf16_f32 v92, v92, v93
	v_cvt_pk_bf16_f32 v93, v94, v95
	global_store_dwordx2 v157, v[92:93], s[16:17]
	s_waitcnt vmcnt(15)
	v_pk_mul_f32 v[88:89], v[88:89], v[206:207] op_sel_hi:[1,0]
	v_pk_mul_f32 v[90:91], v[90:91], v[206:207] op_sel_hi:[1,0]
	v_pk_mul_f32 v[88:89], v[164:165], v[88:89]
	v_pk_mul_f32 v[90:91], v[166:167], v[90:91]
	v_lshlrev_b32_e32 v0, 16, v236
	v_and_b32_e32 v1, 0xffff0000, v236
	v_lshlrev_b32_e32 v2, 16, v237
	v_and_b32_e32 v3, 0xffff0000, v237
	v_pk_mul_f32 v[88:89], v[88:89], v[0:1]
	v_pk_mul_f32 v[90:91], v[90:91], v[2:3]
	v_cvt_pk_bf16_f32 v88, v88, v89
	v_cvt_pk_bf16_f32 v89, v90, v91
	global_store_dwordx2 v157, v[88:89], s[16:17] offset:32
	s_waitcnt vmcnt(15)
	v_pk_mul_f32 v[84:85], v[84:85], v[206:207] op_sel_hi:[1,0]
	v_pk_mul_f32 v[86:87], v[86:87], v[206:207] op_sel_hi:[1,0]
	v_pk_mul_f32 v[84:85], v[168:169], v[84:85]
	v_pk_mul_f32 v[86:87], v[170:171], v[86:87]
	v_lshlrev_b32_e32 v0, 16, v238
	v_and_b32_e32 v1, 0xffff0000, v238
	v_lshlrev_b32_e32 v2, 16, v239
	v_and_b32_e32 v3, 0xffff0000, v239
	v_pk_mul_f32 v[84:85], v[84:85], v[0:1]
	v_pk_mul_f32 v[86:87], v[86:87], v[2:3]
	v_cvt_pk_bf16_f32 v84, v84, v85
	v_cvt_pk_bf16_f32 v85, v86, v87
	global_store_dwordx2 v157, v[84:85], s[16:17] offset:64
	s_waitcnt vmcnt(15)
	v_pk_mul_f32 v[80:81], v[80:81], v[206:207] op_sel_hi:[1,0]
	v_pk_mul_f32 v[82:83], v[82:83], v[206:207] op_sel_hi:[1,0]
	v_pk_mul_f32 v[80:81], v[172:173], v[80:81]
	v_pk_mul_f32 v[82:83], v[174:175], v[82:83]
	v_lshlrev_b32_e32 v0, 16, v240
	v_and_b32_e32 v1, 0xffff0000, v240
	v_lshlrev_b32_e32 v2, 16, v241
	v_and_b32_e32 v3, 0xffff0000, v241
	v_pk_mul_f32 v[80:81], v[80:81], v[0:1]
	v_pk_mul_f32 v[82:83], v[82:83], v[2:3]
	v_cvt_pk_bf16_f32 v80, v80, v81
	v_cvt_pk_bf16_f32 v81, v82, v83
	global_store_dwordx2 v157, v[80:81], s[16:17] offset:96
	s_waitcnt vmcnt(15)
	v_pk_mul_f32 v[76:77], v[76:77], v[206:207] op_sel_hi:[1,0]
	v_pk_mul_f32 v[78:79], v[78:79], v[206:207] op_sel_hi:[1,0]
	v_pk_mul_f32 v[76:77], v[96:97], v[76:77]
	v_pk_mul_f32 v[78:79], v[98:99], v[78:79]
	v_lshlrev_b32_e32 v0, 16, v242
	v_and_b32_e32 v1, 0xffff0000, v242
	v_lshlrev_b32_e32 v2, 16, v243
	v_and_b32_e32 v3, 0xffff0000, v243
	v_pk_mul_f32 v[76:77], v[76:77], v[0:1]
	v_pk_mul_f32 v[78:79], v[78:79], v[2:3]
	v_cvt_pk_bf16_f32 v76, v76, v77
	v_cvt_pk_bf16_f32 v77, v78, v79
	global_store_dwordx2 v157, v[76:77], s[16:17] offset:128
	s_waitcnt vmcnt(15)
	v_pk_mul_f32 v[72:73], v[72:73], v[206:207] op_sel_hi:[1,0]
	v_pk_mul_f32 v[74:75], v[74:75], v[206:207] op_sel_hi:[1,0]
	v_pk_mul_f32 v[72:73], v[100:101], v[72:73]
	v_pk_mul_f32 v[74:75], v[102:103], v[74:75]
	v_lshlrev_b32_e32 v0, 16, v244
	v_and_b32_e32 v1, 0xffff0000, v244
	v_lshlrev_b32_e32 v2, 16, v245
	v_and_b32_e32 v3, 0xffff0000, v245
	v_pk_mul_f32 v[72:73], v[72:73], v[0:1]
	v_pk_mul_f32 v[74:75], v[74:75], v[2:3]
	v_cvt_pk_bf16_f32 v72, v72, v73
	v_cvt_pk_bf16_f32 v73, v74, v75
	global_store_dwordx2 v157, v[72:73], s[16:17] offset:160
	s_waitcnt vmcnt(15)
	v_pk_mul_f32 v[68:69], v[68:69], v[206:207] op_sel_hi:[1,0]
	v_pk_mul_f32 v[70:71], v[70:71], v[206:207] op_sel_hi:[1,0]
	v_pk_mul_f32 v[68:69], v[104:105], v[68:69]
	v_pk_mul_f32 v[70:71], v[106:107], v[70:71]
	v_lshlrev_b32_e32 v0, 16, v246
	v_and_b32_e32 v1, 0xffff0000, v246
	v_lshlrev_b32_e32 v2, 16, v247
	v_and_b32_e32 v3, 0xffff0000, v247
	v_pk_mul_f32 v[68:69], v[68:69], v[0:1]
	v_pk_mul_f32 v[70:71], v[70:71], v[2:3]
	v_cvt_pk_bf16_f32 v68, v68, v69
	v_cvt_pk_bf16_f32 v69, v70, v71
	global_store_dwordx2 v157, v[68:69], s[16:17] offset:192
	s_waitcnt vmcnt(15)
	v_pk_mul_f32 v[64:65], v[64:65], v[206:207] op_sel_hi:[1,0]
	v_pk_mul_f32 v[66:67], v[66:67], v[206:207] op_sel_hi:[1,0]
	v_pk_mul_f32 v[64:65], v[108:109], v[64:65]
	v_pk_mul_f32 v[66:67], v[110:111], v[66:67]
	v_lshlrev_b32_e32 v0, 16, v248
	v_and_b32_e32 v1, 0xffff0000, v248
	v_lshlrev_b32_e32 v2, 16, v249
	v_and_b32_e32 v3, 0xffff0000, v249
	v_pk_mul_f32 v[64:65], v[64:65], v[0:1]
	v_pk_mul_f32 v[66:67], v[66:67], v[2:3]
	v_cvt_pk_bf16_f32 v64, v64, v65
	v_cvt_pk_bf16_f32 v65, v66, v67
	global_store_dwordx2 v157, v[64:65], s[16:17] offset:224
	ds_read_b128 v[0:3], v218 offset:8192
	ds_read_b128 v[4:7], v218 offset:9216
	ds_read_b128 v[8:11], v218 offset:10240
	ds_read_b128 v[12:15], v218 offset:11264
	ds_read_b128 v[16:19], v218 offset:12288
	ds_read_b128 v[20:23], v218 offset:13312
	ds_read_b128 v[24:27], v218 offset:14336
	ds_read_b128 v[28:31], v218 offset:15360
	v_div_scale_f32 v219, s[6:7], v146, v146, 1.0
	v_rcp_f32_e32 v231, v219
	v_div_scale_f32 v232, vcc, 1.0, v146, 1.0
	v_fma_f32 v212, -v219, v231, 1.0
	v_fmac_f32_e32 v231, v212, v231
	v_mul_f32_e32 v213, v232, v231
	v_fma_f32 v212, -v219, v213, v232
	v_fmac_f32_e32 v213, v212, v231
	v_fma_f32 v212, -v219, v213, v232
	s_nop 0
	v_div_fmas_f32 v212, v212, v231, v213
	v_div_fixup_f32 v220, v212, v146, 1.0
	s_waitcnt lgkmcnt(7)
; DI void diff_item(const Params& p, int b, int h, int qb, float lam, char* smem, int tid) {
;     ...
;       for (int qt = 0; qt < 2; ++qt) {
;         const float i1 = 1.f / (qt ? lb : la);
;         f32x4 ov[8];
;         float ss = 0.f;
; #pragma unroll
;         for (int dt = 0; dt < 8; ++dt) {
;           ov[dt] = (qt ? o1[dt] : o0[dt]) * i1 - X[((qg * 2 + qt) * 8 + dt) * 64 + lane];
;           ss += ov[dt][0] * ov[dt][0] + ov[dt][1] * ov[dt][1] + ov[dt][2] * ov[dt][2] + ov[dt][3] * ov[dt][3];
;         }
;         ss += __shfl_xor(ss, 16); ss += __shfl_xor(ss, 32);
;         const float rn = rsqrtf(ss * (1.f / 128.f) + EPSN) * 0.8f;
;         const size_t t = (size_t)(b * SQ + (qt ? qp1 : qp0));
; #pragma unroll
;         for (int dt = 0; dt < 8; ++dt) {
;           const int d0 = dt * 16 + quad * 4;
;           float4 g = *(const float4*)(p.diff_g + d0);
;           uint2 z = *(const uint2*)(p.Za + t * 1024 + h * 128 + d0);
	v_pk_fma_f32 v[60:61], v[60:61], v[220:221], v[0:1] op_sel_hi:[1,0,1] neg_lo:[0,0,1] neg_hi:[0,0,1]
	v_pk_fma_f32 v[62:63], v[62:63], v[220:221], v[2:3] op_sel_hi:[1,0,1] neg_lo:[0,0,1] neg_hi:[0,0,1]
	v_pk_mul_f32 v[210:211], v[60:61], v[60:61]
	v_pk_fma_f32 v[210:211], v[62:63], v[62:63], v[210:211]
	s_waitcnt lgkmcnt(6)
	v_pk_fma_f32 v[56:57], v[56:57], v[220:221], v[4:5] op_sel_hi:[1,0,1] neg_lo:[0,0,1] neg_hi:[0,0,1]
	v_pk_fma_f32 v[58:59], v[58:59], v[220:221], v[6:7] op_sel_hi:[1,0,1] neg_lo:[0,0,1] neg_hi:[0,0,1]
	v_pk_fma_f32 v[210:211], v[56:57], v[56:57], v[210:211]
	v_pk_fma_f32 v[210:211], v[58:59], v[58:59], v[210:211]
	s_waitcnt lgkmcnt(5)
	v_pk_fma_f32 v[52:53], v[52:53], v[220:221], v[8:9] op_sel_hi:[1,0,1] neg_lo:[0,0,1] neg_hi:[0,0,1]
	v_pk_fma_f32 v[54:55], v[54:55], v[220:221], v[10:11] op_sel_hi:[1,0,1] neg_lo:[0,0,1] neg_hi:[0,0,1]
	v_pk_fma_f32 v[210:211], v[52:53], v[52:53], v[210:211]
	v_pk_fma_f32 v[210:211], v[54:55], v[54:55], v[210:211]
	s_waitcnt lgkmcnt(4)
	v_pk_fma_f32 v[48:49], v[48:49], v[220:221], v[12:13] op_sel_hi:[1,0,1] neg_lo:[0,0,1] neg_hi:[0,0,1]
	v_pk_fma_f32 v[50:51], v[50:51], v[220:221], v[14:15] op_sel_hi:[1,0,1] neg_lo:[0,0,1] neg_hi:[0,0,1]
	v_pk_fma_f32 v[210:211], v[48:49], v[48:49], v[210:211]
	v_pk_fma_f32 v[210:211], v[50:51], v[50:51], v[210:211]
	s_waitcnt lgkmcnt(3)
	v_pk_fma_f32 v[44:45], v[44:45], v[220:221], v[16:17] op_sel_hi:[1,0,1] neg_lo:[0,0,1] neg_hi:[0,0,1]
	v_pk_fma_f32 v[46:47], v[46:47], v[220:221], v[18:19] op_sel_hi:[1,0,1] neg_lo:[0,0,1] neg_hi:[0,0,1]
	v_pk_fma_f32 v[210:211], v[44:45], v[44:45], v[210:211]
	v_pk_fma_f32 v[210:211], v[46:47], v[46:47], v[210:211]
	s_waitcnt lgkmcnt(2)
	v_pk_fma_f32 v[40:41], v[40:41], v[220:221], v[20:21] op_sel_hi:[1,0,1] neg_lo:[0,0,1] neg_hi:[0,0,1]
	v_pk_fma_f32 v[42:43], v[42:43], v[220:221], v[22:23] op_sel_hi:[1,0,1] neg_lo:[0,0,1] neg_hi:[0,0,1]
	v_pk_fma_f32 v[210:211], v[40:41], v[40:41], v[210:211]
	v_pk_fma_f32 v[210:211], v[42:43], v[42:43], v[210:211]
	s_waitcnt lgkmcnt(1)
	v_pk_fma_f32 v[36:37], v[36:37], v[220:221], v[24:25] op_sel_hi:[1,0,1] neg_lo:[0,0,1] neg_hi:[0,0,1]
	v_pk_fma_f32 v[38:39], v[38:39], v[220:221], v[26:27] op_sel_hi:[1,0,1] neg_lo:[0,0,1] neg_hi:[0,0,1]
	v_pk_fma_f32 v[210:211], v[36:37], v[36:37], v[210:211]
	v_pk_fma_f32 v[210:211], v[38:39], v[38:39], v[210:211]
	s_waitcnt lgkmcnt(0)
	v_pk_fma_f32 v[32:33], v[32:33], v[220:221], v[28:29] op_sel_hi:[1,0,1] neg_lo:[0,0,1] neg_hi:[0,0,1]
	v_pk_fma_f32 v[34:35], v[34:35], v[220:221], v[30:31] op_sel_hi:[1,0,1] neg_lo:[0,0,1] neg_hi:[0,0,1]
	v_pk_fma_f32 v[210:211], v[32:33], v[32:33], v[210:211]
	v_pk_fma_f32 v[210:211], v[34:35], v[34:35], v[210:211]
	v_add_f32_e32 v212, v210, v211
	ds_bpermute_b32 v213, v148, v212
	s_waitcnt lgkmcnt(0)
	v_add_f32_e32 v212, v212, v213
	ds_bpermute_b32 v213, v149, v212
	s_waitcnt lgkmcnt(0)
	v_add_f32_e32 v212, v212, v213
	v_fmamk_f32 v212, v212, 0x3c000000, v194
	v_rsq_f32_e32 v206, v212
	s_nop 0
	v_mul_f32_e32 v206, 0x3f4ccccd, v206
	s_waitcnt vmcnt(15)
	v_pk_mul_f32 v[60:61], v[60:61], v[206:207] op_sel_hi:[1,0]
	v_pk_mul_f32 v[62:63], v[62:63], v[206:207] op_sel_hi:[1,0]
	v_pk_mul_f32 v[60:61], v[160:161], v[60:61]
	v_pk_mul_f32 v[62:63], v[162:163], v[62:63]
	v_lshlrev_b32_e32 v0, 16, v250
	v_and_b32_e32 v1, 0xffff0000, v250
	v_lshlrev_b32_e32 v2, 16, v251
	v_and_b32_e32 v3, 0xffff0000, v251
	v_pk_mul_f32 v[60:61], v[60:61], v[0:1]
	v_pk_mul_f32 v[62:63], v[62:63], v[2:3]
	v_cvt_pk_bf16_f32 v60, v60, v61
	v_cvt_pk_bf16_f32 v61, v62, v63
	global_store_dwordx2 v158, v[60:61], s[16:17]
	s_waitcnt vmcnt(15)
; DI unsigned pk2(float a, float b) { f32x2 v = {a, b}; bf16x2_t r = __builtin_convertvector(v, bf16x2_t); return __builtin_bit_cast(unsigned, r); }
; DI float bflo(unsigned w) { return __uint_as_float(w << 16); }
; DI float bfhi(unsigned w) { return __uint_as_float(w & 0xffff0000u); }
; DI void diff_item(const Params& p, int b, int h, int qb, float lam, char* smem, int tid) {
;     ...
; #pragma unroll
;         for (int dt = 0; dt < 8; ++dt) {
;           const int d0 = dt * 16 + quad * 4;
;           float4 g = *(const float4*)(p.diff_g + d0);
;           uint2 z = *(const uint2*)(p.Za + t * 1024 + h * 128 + d0);
;           float v0 = ov[dt][0] * rn * g.x * bflo(z.x), v1 = ov[dt][1] * rn * g.y * bfhi(z.x);
;           float v2 = ov[dt][2] * rn * g.z * bflo(z.y), v3 = ov[dt][3] * rn * g.w * bfhi(z.y);
;           uint2 w = {pk2(v0, v1), pk2(v2, v3)};
;           *(uint2*)(p.H + t * DM + h * 128 + d0) = w;
;         }
;       }
	v_pk_mul_f32 v[56:57], v[56:57], v[206:207] op_sel_hi:[1,0]
	v_pk_mul_f32 v[58:59], v[58:59], v[206:207] op_sel_hi:[1,0]
	v_pk_mul_f32 v[56:57], v[164:165], v[56:57]
	v_pk_mul_f32 v[58:59], v[166:167], v[58:59]
	v_lshlrev_b32_e32 v0, 16, v252
	v_and_b32_e32 v1, 0xffff0000, v252
	v_lshlrev_b32_e32 v2, 16, v253
	v_and_b32_e32 v3, 0xffff0000, v253
	v_pk_mul_f32 v[56:57], v[56:57], v[0:1]
	v_pk_mul_f32 v[58:59], v[58:59], v[2:3]
	v_cvt_pk_bf16_f32 v56, v56, v57
	v_cvt_pk_bf16_f32 v57, v58, v59
	global_store_dwordx2 v158, v[56:57], s[16:17] offset:32
	s_waitcnt vmcnt(15)
	v_pk_mul_f32 v[52:53], v[52:53], v[206:207] op_sel_hi:[1,0]
	v_pk_mul_f32 v[54:55], v[54:55], v[206:207] op_sel_hi:[1,0]
	v_pk_mul_f32 v[52:53], v[168:169], v[52:53]
	v_pk_mul_f32 v[54:55], v[170:171], v[54:55]
	v_lshlrev_b32_e32 v0, 16, v184
	v_and_b32_e32 v1, 0xffff0000, v184
	v_lshlrev_b32_e32 v2, 16, v185
	v_and_b32_e32 v3, 0xffff0000, v185
	v_pk_mul_f32 v[52:53], v[52:53], v[0:1]
	v_pk_mul_f32 v[54:55], v[54:55], v[2:3]
	v_cvt_pk_bf16_f32 v52, v52, v53
	v_cvt_pk_bf16_f32 v53, v54, v55
	global_store_dwordx2 v158, v[52:53], s[16:17] offset:64
	s_waitcnt vmcnt(15)
	v_pk_mul_f32 v[48:49], v[48:49], v[206:207] op_sel_hi:[1,0]
	v_pk_mul_f32 v[50:51], v[50:51], v[206:207] op_sel_hi:[1,0]
	v_pk_mul_f32 v[48:49], v[172:173], v[48:49]
	v_pk_mul_f32 v[50:51], v[174:175], v[50:51]
	v_lshlrev_b32_e32 v0, 16, v186
	v_and_b32_e32 v1, 0xffff0000, v186
	v_lshlrev_b32_e32 v2, 16, v187
	v_and_b32_e32 v3, 0xffff0000, v187
	v_pk_mul_f32 v[48:49], v[48:49], v[0:1]
	v_pk_mul_f32 v[50:51], v[50:51], v[2:3]
	v_cvt_pk_bf16_f32 v48, v48, v49
	v_cvt_pk_bf16_f32 v49, v50, v51
	global_store_dwordx2 v158, v[48:49], s[16:17] offset:96
	s_waitcnt vmcnt(15)
	v_pk_mul_f32 v[44:45], v[44:45], v[206:207] op_sel_hi:[1,0]
	v_pk_mul_f32 v[46:47], v[46:47], v[206:207] op_sel_hi:[1,0]
	v_pk_mul_f32 v[44:45], v[96:97], v[44:45]
	v_pk_mul_f32 v[46:47], v[98:99], v[46:47]
	v_lshlrev_b32_e32 v0, 16, v188
	v_and_b32_e32 v1, 0xffff0000, v188
	v_lshlrev_b32_e32 v2, 16, v189
	v_and_b32_e32 v3, 0xffff0000, v189
	v_pk_mul_f32 v[44:45], v[44:45], v[0:1]
	v_pk_mul_f32 v[46:47], v[46:47], v[2:3]
	v_cvt_pk_bf16_f32 v44, v44, v45
	v_cvt_pk_bf16_f32 v45, v46, v47
	global_store_dwordx2 v158, v[44:45], s[16:17] offset:128
	s_waitcnt vmcnt(15)
	v_pk_mul_f32 v[40:41], v[40:41], v[206:207] op_sel_hi:[1,0]
	v_pk_mul_f32 v[42:43], v[42:43], v[206:207] op_sel_hi:[1,0]
	v_pk_mul_f32 v[40:41], v[100:101], v[40:41]
	v_pk_mul_f32 v[42:43], v[102:103], v[42:43]
	v_lshlrev_b32_e32 v0, 16, v208
	v_and_b32_e32 v1, 0xffff0000, v208
	v_lshlrev_b32_e32 v2, 16, v209
	v_and_b32_e32 v3, 0xffff0000, v209
	v_pk_mul_f32 v[40:41], v[40:41], v[0:1]
	v_pk_mul_f32 v[42:43], v[42:43], v[2:3]
	v_cvt_pk_bf16_f32 v40, v40, v41
	v_cvt_pk_bf16_f32 v41, v42, v43
	global_store_dwordx2 v158, v[40:41], s[16:17] offset:160
	s_waitcnt vmcnt(15)
	v_pk_mul_f32 v[36:37], v[36:37], v[206:207] op_sel_hi:[1,0]
	v_pk_mul_f32 v[38:39], v[38:39], v[206:207] op_sel_hi:[1,0]
	v_pk_mul_f32 v[36:37], v[104:105], v[36:37]
	v_pk_mul_f32 v[38:39], v[106:107], v[38:39]
	v_lshlrev_b32_e32 v0, 16, v214
	v_and_b32_e32 v1, 0xffff0000, v214
	v_lshlrev_b32_e32 v2, 16, v215
	v_and_b32_e32 v3, 0xffff0000, v215
	v_pk_mul_f32 v[36:37], v[36:37], v[0:1]
	v_pk_mul_f32 v[38:39], v[38:39], v[2:3]
	v_cvt_pk_bf16_f32 v36, v36, v37
	v_cvt_pk_bf16_f32 v37, v38, v39
	global_store_dwordx2 v158, v[36:37], s[16:17] offset:192
	s_waitcnt vmcnt(15)
	v_pk_mul_f32 v[32:33], v[32:33], v[206:207] op_sel_hi:[1,0]
	v_pk_mul_f32 v[34:35], v[34:35], v[206:207] op_sel_hi:[1,0]
	v_pk_mul_f32 v[32:33], v[108:109], v[32:33]
	v_pk_mul_f32 v[34:35], v[110:111], v[34:35]
	v_lshlrev_b32_e32 v0, 16, v216
	v_and_b32_e32 v1, 0xffff0000, v216
	v_lshlrev_b32_e32 v2, 16, v217
	v_and_b32_e32 v3, 0xffff0000, v217
	v_pk_mul_f32 v[32:33], v[32:33], v[0:1]
	v_pk_mul_f32 v[34:35], v[34:35], v[2:3]
	v_cvt_pk_bf16_f32 v32, v32, v33
	v_cvt_pk_bf16_f32 v33, v34, v35
	global_store_dwordx2 v158, v[32:33], s[16:17] offset:224
	v_mov_b32_e32 v183, v179
	v_mov_b32_e32 v181, v179

; DI void phase_nsa(const Params& p, char* smem, int tid0) {
;   int tid = tid0;
;   int* s_item = (int*)(smem + SMEM_BYTES - 16);
;   int nxt = 0;
;   if (tid == 0) nxt = atomicAdd(p.ctr + 1, 1);
;   for (;;) {
;     __syncthreads();
;     if (tid == 0) *s_item = nxt;
;     __syncthreads();
;     const int it = *s_item;
;     if (it >= 2048) break;
;     if (tid == 0) nxt = atomicAdd(p.ctr + 1, 1);
.LBB0_724:
	s_or_b64 exec, exec, s[0:1]
	v_mov_b32_e32 v199, v197
	s_barrier
	v_mov_b32_e32 v201, 0
	v_cmp_eq_u32_e32 vcc, 0, v199
	v_mov_b64_e32 v[206:207], s[34:35]
	s_and_saveexec_b64 s[0:1], vcc
	s_cbranch_execz .LBB0_728
	s_mov_b64 s[4:5], exec
	v_mbcnt_lo_u32_b32 v0, s4, 0
	v_mbcnt_hi_u32_b32 v0, s5, v0
	v_cmp_eq_u32_e32 vcc, 0, v0
	v_mov_b64_e32 v[206:207], s[34:35]
	s_and_saveexec_b64 s[2:3], vcc
	s_cbranch_execz .LBB0_727
	s_bcnt1_i32_b64 s4, s[4:5]
	s_and_b32 s5, s90, 7
	s_lshl_b32 s5, s5, 2
	v_mov_b32_e32 v1, s5
	v_mov_b32_e32 v2, s4
	global_atomic_add v1, v1, v2, s[34:35] offset:80 sc0
	v_mov_b64_e32 v[206:207], s[34:35]

; DI void phase_nsa(const Params& p, char* smem, int tid0) {
;     ...
;   if (tid == 0) nxt = atomicAdd(p.ctr + 1, 1);
;   for (;;) {
;     __syncthreads();
;     if (tid == 0) *s_item = nxt;
;     __syncthreads();
;     const int it = *s_item;
;     if (it >= 2048) break;
;     if (tid == 0) nxt = atomicAdd(p.ctr + 1, 1);
;     asm volatile("" : "+v"(tid));
;     const int kk = it & 7;
;     nsa_item(p, kk >> 1, kk & 1, 255 - (it >> 3), smem, tid);
.LBB0_728:
	s_or_b64 exec, exec, s[0:1]
	s_and_b32 s0, s90, 7
	s_lshl_b32 s0, s0, 2
	s_mov_b32 s1, 0
	v_lshl_add_u64 v[206:207], s[0:1], 0, v[206:207]
	s_add_i32 s0, 0, 0x20004
	v_writelane_b32 v255, s0, 8
	v_writelane_b32 v255, s90, 9
	s_load_dwordx4 s[60:63], s[92:93], 0x148
	s_load_dwordx8 s[64:71], s[92:93], 0x110
	v_writelane_b32 v255, s92, 10
	s_add_i32 s72, 0, 0x247f0
	s_add_i32 s76, 0, 0x20000
	v_writelane_b32 v255, s93, 11
	v_writelane_b32 v255, s94, 12
	s_mov_b32 s1, 0
	v_mov_b32_e32 v203, s72
	v_writelane_b32 v255, s95, 13
	s_waitcnt lgkmcnt(0)
	v_writelane_b32 v255, s60, 14
	s_movk_i32 s73, 0x7ff
	v_mov_b32_e32 v205, 1
	v_writelane_b32 v255, s61, 15
	v_writelane_b32 v255, s62, 16
	v_writelane_b32 v255, s63, 17
	v_writelane_b32 v255, s64, 18
	v_mov_b32_e32 v17, 0
	s_movk_i32 s74, 0x60
	v_writelane_b32 v255, s65, 19
	v_writelane_b32 v255, s66, 20
	v_writelane_b32 v255, s67, 21
	v_writelane_b32 v255, s68, 22
	v_writelane_b32 v255, s69, 23
	v_writelane_b32 v255, s70, 24
	v_writelane_b32 v255, s71, 25
	v_writelane_b32 v255, s72, 26
	s_movk_i32 s75, 0x1080
	s_movk_i32 s77, 0xe7f
	s_movk_i32 s78, 0x80
	s_movk_i32 s79, 0xf0
	s_movk_i32 s80, 0x70
	s_mov_b64 s[82:83], 0x80
	s_mov_b32 s81, 0x10000
	s_mov_b32 s40, 0x3e0293ee
	s_mov_b32 s41, 0xf149f2ca
	s_mov_b32 s33, 0xefa18f08
	s_movk_i32 s84, 0x210
	v_mov_b32_e32 v231, 0xf149f2ca
	v_mov_b32_e32 v232, 0x461c4000
	v_writelane_b32 v255, s76, 27
	s_branch .LBB0_732

; DI void phase_nsa(const Params& p, char* smem, int tid0) {
;     ...
;   for (;;) {
;     __syncthreads();
;     if (tid == 0) *s_item = nxt;
;     __syncthreads();
;     const int it = *s_item;
;     if (it >= 2048) break;
;     if (tid == 0) nxt = atomicAdd(p.ctr + 1, 1);
.LBB0_732:
	v_cmp_eq_u32_e64 s[4:5], 0, v199
	s_barrier
	s_and_saveexec_b64 s[2:3], s[4:5]
	v_readlane_b32 s0, v255, 9
	v_mov_b32_e32 v0, s72
	s_and_b32 s0, s0, 7
	s_nop 0
	v_lshl_or_b32 v201, v201, 3, s0
	ds_write_b32 v0, v201
	s_or_b64 exec, exec, s[2:3]
	s_waitcnt lgkmcnt(0)
	s_barrier
	ds_read_b32 v0, v203
	s_mov_b64 s[2:3], -1
	s_waitcnt lgkmcnt(0)
	v_cmp_lt_i32_e32 vcc, s73, v0
	v_readfirstlane_b32 s0, v0
	s_cbranch_vccnz .LBB0_731
	s_and_saveexec_b64 s[2:3], s[4:5]
	s_cbranch_execz .LBB0_737
	global_atomic_add v201, v[206:207], v205, off offset:80 sc0
